# PEER top-k: early-exit ballot threshold search, DPP wave sum; gather-loop transpose-reduce via DPP; GEMM counted waits; med3 insertion
# speedup vs baseline: 1.0330x; 1.0176x over previous
.LBB0_297:
	s_movk_i32 s0, 0x5f
	s_waitcnt lgkmcnt(0)
	v_readfirstlane_b32 s100, v0
	v_cmp_lt_i32_e32 vcc, s0, v0
	s_cbranch_vccnz .LBB0_296
	v_ashrrev_i32_e32 v2, 31, v0
	v_lshrrev_b32_e32 v2, 28, v2
	v_add_u32_e32 v2, v0, v2
	v_ashrrev_i32_e32 v3, 4, v2
	v_and_b32_e32 v2, -16, v2
	v_sub_u32_e32 v186, v0, v2
	v_add_u32_e32 v0, s94, v3
	v_mov_b32_e32 v2, s95
	v_mov_b32_e32 v3, s96
	v_cmp_gt_i32_e32 vcc, 16, v0
	v_lshlrev_b32_e32 v154, 7, v186
	v_ashrrev_i32_e32 v155, 31, v154
	v_cndmask_b32_e32 v2, v2, v3, vcc
	v_add_u32_e32 v0, v0, v2
	s_waitcnt vmcnt(0)
	v_lshlrev_b32_e32 v156, 7, v0
	v_ashrrev_i32_e32 v157, 31, v156
	v_lshlrev_b64 v[16:17], 11, v[156:157]
	v_lshl_add_u64 v[6:7], v[132:133], 0, v[16:17]
	v_lshlrev_b64 v[18:19], 11, v[154:155]
	v_add_co_u32_e32 v10, vcc, s54, v6
	v_lshl_add_u64 v[8:9], v[134:135], 0, v[18:19]
	s_nop 0
	v_addc_co_u32_e32 v11, vcc, 0, v7, vcc
	v_add_co_u32_e32 v12, vcc, s54, v8
	global_load_dwordx4 v[70:73], v[6:7], off
	global_load_dwordx4 v[66:69], v[8:9], off
	v_addc_co_u32_e32 v13, vcc, 0, v9, vcc
	v_add_co_u32_e32 v14, vcc, s55, v6
	global_load_dwordx4 v[74:77], v[10:11], off
	global_load_dwordx4 v[78:81], v[12:13], off
	v_addc_co_u32_e32 v15, vcc, 0, v7, vcc
	v_add_co_u32_e32 v20, vcc, s55, v8
	global_load_dwordx4 v[86:89], v[14:15], off
	s_nop 0
	v_addc_co_u32_e32 v21, vcc, 0, v9, vcc
	v_add_co_u32_e32 v22, vcc, s56, v8
	global_load_dwordx4 v[82:85], v[20:21], off
	s_nop 0
	v_addc_co_u32_e32 v23, vcc, 0, v9, vcc
	v_add_co_u32_e32 v24, vcc, s56, v6
	global_load_dwordx4 v[90:93], v[22:23], off
	s_nop 0
	v_addc_co_u32_e32 v25, vcc, 0, v7, vcc
	global_load_dwordx4 v[94:97], v[24:25], off
	global_load_dwordx4 v[98:101], v[8:9], off offset:128
	global_load_dwordx4 v[106:109], v[12:13], off offset:128
	global_load_dwordx4 v[114:117], v[20:21], off offset:128
	global_load_dwordx4 v[122:125], v[22:23], off offset:128
	global_load_dwordx4 v[102:105], v[6:7], off offset:128
	global_load_dwordx4 v[110:113], v[10:11], off offset:128
	global_load_dwordx4 v[118:121], v[14:15], off offset:128
	global_load_dwordx4 v[126:129], v[24:25], off offset:128
	v_mov_b32_e32 v2, 0
	s_mov_b32 s4, -2
	v_mov_b32_e32 v3, v2
	v_mov_b32_e32 v4, v2
	v_mov_b32_e32 v5, v2
	v_mov_b32_e32 v6, v2
	v_mov_b32_e32 v7, v2
	v_mov_b32_e32 v8, v2
	v_mov_b32_e32 v9, v2
	v_mov_b32_e32 v10, v2
	v_mov_b32_e32 v11, v2
	v_mov_b32_e32 v12, v2
	v_mov_b32_e32 v13, v2
	v_mov_b32_e32 v14, v2
	v_mov_b32_e32 v15, v2
	v_lshl_add_u64 v[158:159], v[140:141], 0, v[18:19]
	v_lshl_add_u64 v[162:163], v[142:143], 0, v[18:19]
	v_lshl_add_u64 v[164:165], v[144:145], 0, v[18:19]
	v_lshl_add_u64 v[166:167], v[148:149], 0, v[18:19]
	v_lshl_add_u64 v[168:169], v[150:151], 0, v[18:19]
	v_lshl_add_u64 v[170:171], v[152:153], 0, v[18:19]
	v_lshl_add_u64 v[172:173], v[146:147], 0, v[16:17]
	v_mov_b32_e32 v16, v2
	v_mov_b32_e32 v17, v2
	v_mov_b32_e32 v18, v2
	v_mov_b32_e32 v19, v2
	v_mov_b32_e32 v20, v2
	v_mov_b32_e32 v21, v2
	v_mov_b32_e32 v22, v2
	v_mov_b32_e32 v23, v2
	v_mov_b32_e32 v24, v2
	v_mov_b32_e32 v25, v2
	v_mov_b32_e32 v26, v2
	v_mov_b32_e32 v27, v2
	v_mov_b32_e32 v28, v2
	v_mov_b32_e32 v29, v2
	v_mov_b32_e32 v30, v2
	v_mov_b32_e32 v31, v2
	v_mov_b32_e32 v32, v2
	v_mov_b32_e32 v33, v2
	v_mov_b32_e32 v34, v2
	v_mov_b32_e32 v35, v2
	v_mov_b32_e32 v36, v2
	v_mov_b32_e32 v37, v2
	v_mov_b32_e32 v38, v2
	v_mov_b32_e32 v39, v2
	v_mov_b32_e32 v40, v2
	v_mov_b32_e32 v41, v2
	v_mov_b32_e32 v42, v2
	v_mov_b32_e32 v43, v2
	v_mov_b32_e32 v44, v2
	v_mov_b32_e32 v45, v2
	v_mov_b32_e32 v46, v2
	v_mov_b32_e32 v47, v2
	v_mov_b32_e32 v48, v2
	v_mov_b32_e32 v49, v2
	v_mov_b32_e32 v50, v2
	v_mov_b32_e32 v51, v2
	v_mov_b32_e32 v52, v2
	v_mov_b32_e32 v53, v2
	v_mov_b32_e32 v54, v2
	v_mov_b32_e32 v55, v2
	v_mov_b32_e32 v56, v2
	v_mov_b32_e32 v57, v2
	v_mov_b32_e32 v58, v2
	v_mov_b32_e32 v59, v2
	v_mov_b32_e32 v60, v2
	v_mov_b32_e32 v61, v2
	v_mov_b32_e32 v62, v2
	v_mov_b32_e32 v63, v2
	v_mov_b32_e32 v64, v2
	v_mov_b32_e32 v65, v2
	s_waitcnt vmcnt(14)
	ds_write_b128 v182, v[66:69] offset:36864
	s_waitcnt vmcnt(12)
	ds_write_b128 v182, v[78:81] offset:41472
	s_waitcnt vmcnt(10)
	ds_write_b128 v182, v[82:85] offset:46080
	s_waitcnt vmcnt(9)
	ds_write_b128 v182, v[90:93] offset:50688
	ds_write_b128 v182, v[70:73]
	ds_write_b128 v182, v[74:77] offset:4608
	ds_write_b128 v182, v[86:89] offset:9216
	s_waitcnt vmcnt(8)
	ds_write_b128 v182, v[94:97] offset:13824
	s_waitcnt lgkmcnt(0)
	s_barrier
	s_branch .LBB0_300

.LBB0_410:
	s_or_b64 exec, exec, s[0:1]
	s_lshl_b32 s101, s33, 1
	s_cmp_lt_u32 s101, 96
	s_cbranch_scc1 .Lg1_fetch
	s_cmp_ge_u32 s100, s33
	s_cbranch_scc1 .LBB0_415
.Lg1_fetch:
	s_waitcnt vmcnt(63) expcnt(7) lgkmcnt(15)
	s_barrier
	s_and_saveexec_b64 s[0:1], s[14:15]
	s_xor_b64 s[0:1], exec, s[0:1]
	s_cbranch_execz .LBB0_414
	s_mov_b64 s[4:5], exec
	v_mbcnt_lo_u32_b32 v0, s4, 0
	v_mbcnt_hi_u32_b32 v0, s5, v0
	v_cmp_eq_u32_e32 vcc, 0, v0
	s_and_saveexec_b64 s[2:3], vcc
	s_cbranch_execz .LBB0_413
	s_bcnt1_i32_b64 s4, s[4:5]
	v_mov_b32_e32 v2, s4
	global_atomic_add v2, v1, v2, s[24:25] sc0

.LBB0_552:
	v_cndmask_b32_e64 v2, 0, 1, s[0:1]
	s_mul_i32 s0, s4, 0x2400
	v_add_u32_e32 v11, s0, v175
	v_cmp_ne_u32_e32 vcc, 1, v2
	ds_read_b128 v[2:5], v11
	ds_read_b128 v[6:9], v11 offset:32
	v_mov_b32_e32 v10, v164
	s_waitcnt lgkmcnt(1)
	v_mfma_f32_32x32x16_bf16 v[64:79], v[2:5], v[112:115], 0
	ds_read_b128 v[2:5], v11 offset:4608
	v_mov_b32_e32 v80, v165
	s_and_b64 vcc, exec, vcc
	s_waitcnt lgkmcnt(0)
	v_mfma_f32_32x32x16_bf16 v[48:63], v[2:5], v[112:115], 0
	ds_read_b128 v[2:5], v11 offset:4640
	v_mfma_f32_32x32x16_bf16 v[64:79], v[6:9], v[116:119], v[64:79]
	s_waitcnt lgkmcnt(0)
	v_mfma_f32_32x32x16_bf16 v[48:63], v[2:5], v[116:119], v[48:63]
	s_nop 9
	v_max3_f32 v2, v64, s61, v65
	v_max3_f32 v2, v2, v66, v67
	v_max3_f32 v2, v2, v68, v69
	v_max3_f32 v2, v2, v70, v71
	v_max3_f32 v2, v2, v72, v73
	v_max3_f32 v2, v2, v74, v75
	v_max3_f32 v2, v2, v76, v77
	v_max3_f32 v2, v2, v78, v79
	v_max3_f32 v2, v2, v48, v49
	v_max3_f32 v2, v2, v50, v51
	v_max3_f32 v2, v2, v52, v53
	v_max3_f32 v2, v2, v54, v55
	v_max3_f32 v2, v2, v56, v57
	v_max3_f32 v2, v2, v58, v59
	v_max3_f32 v2, v2, v60, v61
	v_max3_f32 v2, v2, v62, v63
	v_mul_f32_e32 v2, s9, v2
	ds_bpermute_b32 v3, v0, v2
	s_waitcnt lgkmcnt(0)
	v_max3_f32 v164, v10, v2, v3
	v_cmp_eq_f32_e64 s[0:1], s61, v164
	v_sub_f32_e32 v2, v10, v164
	v_exp_f32_e32 v2, v2
	v_cndmask_b32_e64 v3, v164, 0, s[0:1]
	v_fma_f32 v4, s9, v64, -v3
	v_exp_f32_e32 v4, v4
	v_fma_f32 v6, s9, v65, -v3
	v_exp_f32_e32 v64, v6
	v_fma_f32 v6, s9, v66, -v3
	v_exp_f32_e32 v65, v6
	v_fma_f32 v6, s9, v67, -v3
	v_exp_f32_e32 v66, v6
	v_fma_f32 v6, s9, v68, -v3
	v_add_f32_e32 v5, 0, v4
	v_exp_f32_e32 v67, v6
	v_fma_f32 v6, s9, v69, -v3
	v_add_f32_e32 v5, v64, v5
	v_exp_f32_e32 v68, v6
	v_fma_f32 v6, s9, v70, -v3
	v_add_f32_e32 v5, v65, v5
	v_exp_f32_e32 v69, v6
	v_fma_f32 v6, s9, v71, -v3
	v_add_f32_e32 v5, v66, v5
	v_exp_f32_e32 v70, v6
	v_fma_f32 v6, s9, v72, -v3
	v_add_f32_e32 v5, v67, v5
	v_exp_f32_e32 v6, v6
	v_fma_f32 v7, s9, v73, -v3
	v_add_f32_e32 v5, v68, v5
	v_exp_f32_e32 v7, v7
	v_fma_f32 v8, s9, v74, -v3
	v_add_f32_e32 v5, v69, v5
	v_exp_f32_e32 v8, v8
	v_fma_f32 v9, s9, v75, -v3
	v_add_f32_e32 v5, v70, v5
	v_exp_f32_e32 v9, v9
	v_fma_f32 v10, s9, v76, -v3
	v_add_f32_e32 v5, v6, v5
	v_exp_f32_e32 v10, v10
	v_fma_f32 v11, s9, v77, -v3
	v_add_f32_e32 v5, v7, v5
	v_exp_f32_e32 v11, v11
	v_fma_f32 v12, s9, v78, -v3
	v_add_f32_e32 v5, v8, v5
	v_exp_f32_e32 v12, v12
	v_fma_f32 v13, s9, v79, -v3
	v_add_f32_e32 v5, v9, v5
	v_exp_f32_e32 v14, v13
	v_fma_f32 v13, s9, v48, -v3
	v_add_f32_e32 v5, v10, v5
	v_exp_f32_e32 v13, v13
	v_fma_f32 v15, s9, v49, -v3
	v_add_f32_e32 v5, v11, v5
	v_exp_f32_e32 v15, v15
	v_fma_f32 v48, s9, v50, -v3
	v_add_f32_e32 v5, v12, v5
	v_exp_f32_e32 v48, v48
	v_fma_f32 v49, s9, v51, -v3
	v_add_f32_e32 v5, v14, v5
	v_exp_f32_e32 v49, v49
	v_fma_f32 v50, s9, v52, -v3
	v_add_f32_e32 v5, v13, v5
	v_exp_f32_e32 v50, v50
	v_fma_f32 v51, s9, v53, -v3
	v_add_f32_e32 v5, v15, v5
	v_exp_f32_e32 v51, v51
	v_fma_f32 v52, s9, v54, -v3
	v_add_f32_e32 v5, v48, v5
	v_exp_f32_e32 v52, v52
	v_fma_f32 v53, s9, v55, -v3
	v_add_f32_e32 v5, v49, v5
	v_exp_f32_e32 v54, v53
	v_fma_f32 v53, s9, v56, -v3
	v_add_f32_e32 v5, v50, v5
	v_exp_f32_e32 v53, v53
	v_fma_f32 v55, s9, v57, -v3
	v_add_f32_e32 v5, v51, v5
	v_exp_f32_e32 v55, v55
	v_fma_f32 v56, s9, v58, -v3
	v_add_f32_e32 v5, v52, v5
	v_exp_f32_e32 v56, v56
	v_fma_f32 v57, s9, v59, -v3
	v_add_f32_e32 v5, v54, v5
	v_exp_f32_e32 v57, v57
	v_fma_f32 v58, s9, v60, -v3
	v_add_f32_e32 v5, v53, v5
	v_exp_f32_e32 v58, v58
	v_fma_f32 v59, s9, v61, -v3
	v_add_f32_e32 v5, v55, v5
	v_exp_f32_e32 v59, v59
	v_fma_f32 v60, s9, v62, -v3
	v_add_f32_e32 v5, v56, v5
	v_exp_f32_e32 v60, v60
	v_fma_f32 v3, s9, v63, -v3
	v_add_f32_e32 v5, v57, v5
	v_exp_f32_e32 v61, v3
	v_add_f32_e32 v5, v58, v5
	v_add_f32_e32 v5, v59, v5
	v_add_f32_e32 v5, v60, v5
	v_add_f32_e32 v165, v61, v5
	v_cvt_pk_bf16_f32 v5, v69, v70
	v_lshl_add_u32 v70, s4, 7, v174
	v_cndmask_b32_e64 v2, v2, 1.0, s[0:1]
	v_add_u32_e32 v71, 0x4800, v70
	v_fmac_f32_e32 v165, v80, v2
	v_pk_mul_f32 v[46:47], v[46:47], v[2:3] op_sel_hi:[1,0]
	v_pk_mul_f32 v[44:45], v[44:45], v[2:3] op_sel_hi:[1,0]
	v_pk_mul_f32 v[42:43], v[42:43], v[2:3] op_sel_hi:[1,0]
	v_pk_mul_f32 v[40:41], v[40:41], v[2:3] op_sel_hi:[1,0]
	v_pk_mul_f32 v[38:39], v[38:39], v[2:3] op_sel_hi:[1,0]
	v_pk_mul_f32 v[36:37], v[36:37], v[2:3] op_sel_hi:[1,0]
	v_pk_mul_f32 v[34:35], v[34:35], v[2:3] op_sel_hi:[1,0]
	v_pk_mul_f32 v[32:33], v[32:33], v[2:3] op_sel_hi:[1,0]
	v_pk_mul_f32 v[30:31], v[30:31], v[2:3] op_sel_hi:[1,0]
	v_pk_mul_f32 v[28:29], v[28:29], v[2:3] op_sel_hi:[1,0]
	v_pk_mul_f32 v[26:27], v[26:27], v[2:3] op_sel_hi:[1,0]
	v_pk_mul_f32 v[24:25], v[24:25], v[2:3] op_sel_hi:[1,0]
	v_pk_mul_f32 v[22:23], v[22:23], v[2:3] op_sel_hi:[1,0]
	v_pk_mul_f32 v[20:21], v[20:21], v[2:3] op_sel_hi:[1,0]
	v_pk_mul_f32 v[18:19], v[18:19], v[2:3] op_sel_hi:[1,0]
	v_pk_mul_f32 v[16:17], v[16:17], v[2:3] op_sel_hi:[1,0]
	v_cvt_pk_bf16_f32 v2, v4, v64
	v_cvt_pk_bf16_f32 v3, v65, v66
	v_cvt_pk_bf16_f32 v4, v67, v68
	ds_read2_b64 v[62:65], v71 offset1:2
	ds_read2_b64 v[66:69], v71 offset0:4 offset1:6
	v_add_u32_e32 v70, 0x6800, v70
	s_waitcnt lgkmcnt(1)
	v_mfma_f32_32x32x16_bf16 v[32:47], v[62:65], v[2:5], v[32:47]
	ds_read2_b64 v[62:65], v70 offset0:64 offset1:66
	s_mov_b64 s[0:1], 0
	s_mov_b32 s4, 1
	s_waitcnt lgkmcnt(0)
	v_mfma_f32_32x32x16_bf16 v[16:31], v[62:65], v[2:5], v[16:31]
	v_cvt_pk_bf16_f32 v2, v6, v7
	v_cvt_pk_bf16_f32 v3, v8, v9
	ds_read2_b64 v[6:9], v70 offset0:68 offset1:70
	v_cvt_pk_bf16_f32 v4, v10, v11
	v_cvt_pk_bf16_f32 v5, v12, v14
	s_waitcnt lgkmcnt(0)
	s_nop 0
	v_mfma_f32_32x32x16_bf16 v[16:31], v[6:9], v[2:5], v[16:31]
	ds_read2_b64 v[6:9], v71 offset0:8 offset1:10
	v_mfma_f32_32x32x16_bf16 v[32:47], v[66:69], v[2:5], v[32:47]
	v_cvt_pk_bf16_f32 v2, v13, v15
	v_cvt_pk_bf16_f32 v3, v48, v49
	v_cvt_pk_bf16_f32 v4, v50, v51
	v_cvt_pk_bf16_f32 v5, v52, v54
	s_waitcnt lgkmcnt(0)
	s_nop 0
	v_mfma_f32_32x32x16_bf16 v[32:47], v[6:9], v[2:5], v[32:47]
	ds_read2_b64 v[6:9], v70 offset0:72 offset1:74
	s_waitcnt lgkmcnt(0)
	v_mfma_f32_32x32x16_bf16 v[16:31], v[6:9], v[2:5], v[16:31]
	ds_read2_b64 v[6:9], v71 offset0:12 offset1:14
	v_cvt_pk_bf16_f32 v2, v53, v55
	v_cvt_pk_bf16_f32 v3, v56, v57
	v_cvt_pk_bf16_f32 v4, v58, v59
	v_cvt_pk_bf16_f32 v5, v60, v61
	s_waitcnt lgkmcnt(0)
	s_nop 0
	v_mfma_f32_32x32x16_bf16 v[32:47], v[6:9], v[2:5], v[32:47]
	ds_read2_b64 v[6:9], v70 offset0:76 offset1:78
	s_waitcnt lgkmcnt(0)
	v_mfma_f32_32x32x16_bf16 v[16:31], v[6:9], v[2:5], v[16:31]
	s_cbranch_vccz .LBB0_552
	s_nop 7
	v_mov_b64_e32 v[62:63], v[46:47]
	s_nop 1
	v_mov_b64_e32 v[78:79], v[30:31]
	v_mov_b64_e32 v[60:61], v[44:45]
	v_mov_b64_e32 v[58:59], v[42:43]
	v_mov_b64_e32 v[56:57], v[40:41]
	v_mov_b64_e32 v[54:55], v[38:39]
	v_mov_b64_e32 v[52:53], v[36:37]
	v_mov_b64_e32 v[50:51], v[34:35]
	v_mov_b64_e32 v[48:49], v[32:33]
	v_mov_b64_e32 v[76:77], v[28:29]
	v_mov_b64_e32 v[74:75], v[26:27]
	v_mov_b64_e32 v[72:73], v[24:25]
	v_mov_b64_e32 v[70:71], v[22:23]
	v_mov_b64_e32 v[68:69], v[20:21]
	v_mov_b64_e32 v[66:67], v[18:19]
	v_mov_b64_e32 v[64:65], v[16:17]
	v_mov_b32_e32 v7, v164
	v_mov_b32_e32 v8, v165

.LBB0_639:
	v_add_u32_e32 v104, s4, v147
	v_add_u32_e32 v67, 0xfffff000, v104
	v_lshrrev_b32_e32 v67, 10, v67
	v_add_u32_e32 v105, 1, v67
	v_cmp_lt_i32_e32 vcc, s57, v104
	v_readlane_b32 s4, v254, 26
	v_readlane_b32 s5, v254, 27
	v_cndmask_b32_e32 v67, 0, v105, vcc
	v_or_b32_e32 v70, v104, v150
	v_or_b32_e32 v66, s6, v135
	v_add_u32_e32 v67, s40, v67
	v_mov_b64_e32 v[68:69], s[4:5]
	v_ashrrev_i32_e32 v71, 31, v70
	s_waitcnt vmcnt(7)
	v_mad_u64_u32 v[82:83], s[4:5], v67, s63, v[68:69]
	v_lshlrev_b64 v[72:73], 12, v[70:71]
	v_ashrrev_i32_e32 v67, 31, v66
	s_waitcnt vmcnt(6)
	v_lshl_add_u64 v[88:89], s[92:93], 0, v[72:73]
	v_lshlrev_b64 v[66:67], 2, v[66:67]
	v_lshl_add_u64 v[86:87], v[82:83], 0, v[66:67]
	v_lshl_add_u64 v[88:89], v[88:89], 0, v[66:67]
	global_load_dword v110, v[86:87], off
	global_load_dword v82, v[88:89], off
	v_or_b32_e32 v72, 1, v70
	v_ashrrev_i32_e32 v73, 31, v72
	v_lshlrev_b64 v[72:73], 12, v[72:73]
	v_lshl_add_u64 v[90:91], s[92:93], 0, v[72:73]
	s_waitcnt vmcnt(6)
	v_lshl_add_u64 v[98:99], v[90:91], 0, v[66:67]
	v_or_b32_e32 v72, 2, v70
	v_ashrrev_i32_e32 v73, 31, v72
	v_lshlrev_b64 v[72:73], 12, v[72:73]
	v_lshl_add_u64 v[96:97], s[92:93], 0, v[72:73]
	v_or_b32_e32 v72, 3, v70
	v_ashrrev_i32_e32 v73, 31, v72
	v_lshlrev_b64 v[72:73], 12, v[72:73]
	v_lshl_add_u64 v[102:103], s[92:93], 0, v[72:73]
	v_lshl_add_u64 v[90:91], v[102:103], 0, v[66:67]
	v_or_b32_e32 v72, 8, v70
	v_ashrrev_i32_e32 v73, 31, v72
	v_lshlrev_b64 v[72:73], 12, v[72:73]
	s_waitcnt vmcnt(5)
	v_lshl_add_u64 v[106:107], s[92:93], 0, v[72:73]
	v_or_b32_e32 v72, 9, v70
	v_ashrrev_i32_e32 v73, 31, v72
	v_lshlrev_b64 v[72:73], 12, v[72:73]
	v_lshl_add_u64 v[108:109], s[92:93], 0, v[72:73]
	v_lshl_add_u64 v[102:103], v[108:109], 0, v[66:67]
	v_or_b32_e32 v72, 10, v70
	v_ashrrev_i32_e32 v73, 31, v72
	v_lshlrev_b64 v[72:73], 12, v[72:73]
	v_lshl_add_u64 v[100:101], s[92:93], 0, v[72:73]
	v_or_b32_e32 v72, 11, v70
	v_ashrrev_i32_e32 v73, 31, v72
	v_lshlrev_b64 v[72:73], 12, v[72:73]
	v_lshl_add_u64 v[94:95], s[92:93], 0, v[72:73]
	v_lshl_add_u64 v[94:95], v[94:95], 0, v[66:67]
	v_or_b32_e32 v72, 16, v70
	v_ashrrev_i32_e32 v73, 31, v72
	v_lshlrev_b64 v[72:73], 12, v[72:73]
	v_lshl_add_u64 v[92:93], s[92:93], 0, v[72:73]
	v_lshl_add_u64 v[92:93], v[92:93], 0, v[66:67]
	v_or_b32_e32 v72, 17, v70
	v_ashrrev_i32_e32 v73, 31, v72
	v_lshlrev_b64 v[72:73], 12, v[72:73]
	v_lshl_add_u64 v[84:85], s[92:93], 0, v[72:73]
	v_lshl_add_u64 v[84:85], v[84:85], 0, v[66:67]
	v_or_b32_e32 v72, 18, v70
	v_ashrrev_i32_e32 v73, 31, v72
	v_lshlrev_b64 v[72:73], 12, v[72:73]
	v_lshl_add_u64 v[80:81], s[92:93], 0, v[72:73]
	v_or_b32_e32 v72, 19, v70
	v_ashrrev_i32_e32 v73, 31, v72
	v_lshlrev_b64 v[72:73], 12, v[72:73]
	v_lshl_add_u64 v[78:79], s[92:93], 0, v[72:73]
	v_or_b32_e32 v72, 24, v70
	v_ashrrev_i32_e32 v73, 31, v72
	v_lshlrev_b64 v[72:73], 12, v[72:73]
	v_lshl_add_u64 v[76:77], s[92:93], 0, v[72:73]
	v_or_b32_e32 v72, 25, v70
	v_ashrrev_i32_e32 v73, 31, v72
	v_lshlrev_b64 v[72:73], 12, v[72:73]
	v_lshl_add_u64 v[74:75], s[92:93], 0, v[72:73]
	v_lshl_add_u64 v[74:75], v[74:75], 0, v[66:67]
	v_or_b32_e32 v72, 26, v70
	v_ashrrev_i32_e32 v73, 31, v72
	v_lshlrev_b64 v[72:73], 12, v[72:73]
	v_lshl_add_u64 v[72:73], s[92:93], 0, v[72:73]
	v_or_b32_e32 v70, 27, v70
	v_ashrrev_i32_e32 v71, 31, v70
	v_lshlrev_b64 v[70:71], 12, v[70:71]
	v_lshl_add_u64 v[70:71], s[92:93], 0, v[70:71]
	s_waitcnt vmcnt(0)
	v_mul_f32_e32 v82, 0x3fd744fd, v82
	v_fmac_f32_e32 v82, v50, v110
	global_load_dword v50, v[98:99], off
	s_waitcnt vmcnt(0)
	v_mul_f32_e32 v50, 0x3fd744fd, v50
	global_store_dword v[88:89], v82, off
	v_fmac_f32_e32 v50, v51, v110
	v_lshl_add_u64 v[82:83], v[96:97], 0, v[66:67]
	global_store_dword v[98:99], v50, off
	global_load_dword v50, v[82:83], off
	v_lshl_add_u64 v[96:97], v[106:107], 0, v[66:67]
	s_waitcnt vmcnt(0)
	v_mul_f32_e32 v50, 0x3fd744fd, v50
	v_fmac_f32_e32 v50, v52, v110
	global_store_dword v[82:83], v50, off
	global_load_dword v50, v[90:91], off
	s_waitcnt vmcnt(0)
	v_mul_f32_e32 v50, 0x3fd744fd, v50
	v_fmac_f32_e32 v50, v53, v110
	global_store_dword v[90:91], v50, off
	global_load_dword v50, v[96:97], off
	s_waitcnt vmcnt(0)
	v_mul_f32_e32 v50, 0x3fd744fd, v50
	v_fmac_f32_e32 v50, v54, v110
	global_store_dword v[96:97], v50, off
	global_load_dword v50, v[102:103], off
	s_waitcnt vmcnt(0)
	v_mul_f32_e32 v50, 0x3fd744fd, v50
	v_fmac_f32_e32 v50, v55, v110
	v_lshl_add_u64 v[54:55], v[100:101], 0, v[66:67]
	global_store_dword v[102:103], v50, off
	global_load_dword v50, v[54:55], off
	s_waitcnt vmcnt(0)
	v_mul_f32_e32 v50, 0x3fd744fd, v50
	v_fmac_f32_e32 v50, v56, v110
	global_store_dword v[54:55], v50, off
	global_load_dword v50, v[94:95], off
	s_waitcnt vmcnt(0)
	v_mul_f32_e32 v50, 0x3fd744fd, v50
	v_fmac_f32_e32 v50, v57, v110
	global_store_dword v[94:95], v50, off
	global_load_dword v50, v[92:93], off
	v_lshl_add_u64 v[56:57], v[80:81], 0, v[66:67]
	s_waitcnt vmcnt(0)
	v_mul_f32_e32 v50, 0x3fd744fd, v50
	v_fmac_f32_e32 v50, v58, v110
	global_store_dword v[92:93], v50, off
	global_load_dword v50, v[84:85], off
	s_waitcnt vmcnt(0)
	v_mul_f32_e32 v50, 0x3fd744fd, v50
	v_fmac_f32_e32 v50, v59, v110
	global_store_dword v[84:85], v50, off
	global_load_dword v50, v[56:57], off
	v_lshl_add_u64 v[58:59], v[78:79], 0, v[66:67]
	s_waitcnt vmcnt(0)
	v_mul_f32_e32 v50, 0x3fd744fd, v50
	v_fmac_f32_e32 v50, v60, v110
	global_store_dword v[56:57], v50, off
	global_load_dword v50, v[58:59], off
	s_waitcnt vmcnt(0)
	v_mul_f32_e32 v50, 0x3fd744fd, v50
	v_fmac_f32_e32 v50, v61, v110
	v_lshl_add_u64 v[60:61], v[76:77], 0, v[66:67]
	global_store_dword v[58:59], v50, off
	global_load_dword v50, v[60:61], off
	s_waitcnt vmcnt(0)
	v_mul_f32_e32 v50, 0x3fd744fd, v50
	v_fmac_f32_e32 v50, v62, v110
	global_store_dword v[60:61], v50, off
	global_load_dword v50, v[74:75], off
	s_waitcnt vmcnt(0)
	v_mul_f32_e32 v50, 0x3fd744fd, v50
	v_fmac_f32_e32 v50, v63, v110
	global_store_dword v[74:75], v50, off
	v_lshl_add_u64 v[50:51], v[72:73], 0, v[66:67]
	global_load_dword v52, v[50:51], off
	s_waitcnt vmcnt(0)
	v_mul_f32_e32 v52, 0x3fd744fd, v52
	v_fmac_f32_e32 v52, v64, v110
	global_store_dword v[50:51], v52, off
	v_lshl_add_u64 v[52:53], v[70:71], 0, v[66:67]
	global_load_dword v62, v[52:53], off
	s_waitcnt vmcnt(0)
	v_mul_f32_e32 v62, 0x3fd744fd, v62
	v_fmac_f32_e32 v62, v65, v110
	global_store_dword v[52:53], v62, off
	global_load_dword v62, v[86:87], off offset:128
	s_nop 0
	global_load_dword v63, v[88:89], off offset:128
	s_waitcnt vmcnt(0)
	v_mul_f32_e32 v63, 0x3fd744fd, v63
	v_fmac_f32_e32 v63, v34, v62
	global_load_dword v34, v[98:99], off offset:128
	s_waitcnt vmcnt(0)
	v_mul_f32_e32 v34, 0x3fd744fd, v34
	v_fmac_f32_e32 v34, v35, v62
	global_store_dword v[98:99], v34, off offset:128
	global_load_dword v34, v[82:83], off offset:128
	s_waitcnt vmcnt(0)
	v_mul_f32_e32 v34, 0x3fd744fd, v34
	v_fmac_f32_e32 v34, v36, v62
	global_store_dword v[82:83], v34, off offset:128
	global_load_dword v34, v[90:91], off offset:128
	v_or_b32_e32 v36, 32, v104
	v_cmp_lt_i32_e32 vcc, s57, v36
	v_or_b32_e32 v36, v36, v150
	global_store_dword v[88:89], v63, off offset:128
	s_waitcnt vmcnt(1)
	v_mul_f32_e32 v34, 0x3fd744fd, v34
	v_fmac_f32_e32 v34, v37, v62
	global_store_dword v[90:91], v34, off offset:128
	global_load_dword v34, v[96:97], off offset:128
	v_ashrrev_i32_e32 v37, 31, v36
	s_waitcnt vmcnt(0)
	v_mul_f32_e32 v34, 0x3fd744fd, v34
	v_fmac_f32_e32 v34, v38, v62
	global_store_dword v[96:97], v34, off offset:128
	global_load_dword v34, v[102:103], off offset:128
	s_waitcnt vmcnt(0)
	v_mul_f32_e32 v34, 0x3fd744fd, v34
	v_fmac_f32_e32 v34, v39, v62
	global_store_dword v[102:103], v34, off offset:128
	global_load_dword v34, v[54:55], off offset:128
	v_lshlrev_b64 v[38:39], 12, v[36:37]
	s_waitcnt vmcnt(0)
	v_mul_f32_e32 v34, 0x3fd744fd, v34
	v_fmac_f32_e32 v34, v40, v62
	global_store_dword v[54:55], v34, off offset:128
	global_load_dword v34, v[94:95], off offset:128
	s_waitcnt vmcnt(0)
	v_mul_f32_e32 v34, 0x3fd744fd, v34
	v_fmac_f32_e32 v34, v41, v62
	global_store_dword v[94:95], v34, off offset:128
	global_load_dword v34, v[92:93], off offset:128
	v_lshl_add_u64 v[40:41], s[92:93], 0, v[38:39]
	v_or_b32_e32 v38, 1, v36
	v_ashrrev_i32_e32 v39, 31, v38
	v_lshlrev_b64 v[38:39], 12, v[38:39]
	s_waitcnt vmcnt(0)
	v_mul_f32_e32 v34, 0x3fd744fd, v34
	v_fmac_f32_e32 v34, v42, v62
	global_store_dword v[92:93], v34, off offset:128
	global_load_dword v34, v[84:85], off offset:128
	s_waitcnt vmcnt(0)
	v_mul_f32_e32 v34, 0x3fd744fd, v34
	v_fmac_f32_e32 v34, v43, v62
	global_store_dword v[84:85], v34, off offset:128
	global_load_dword v34, v[56:57], off offset:128
	v_lshl_add_u64 v[42:43], s[92:93], 0, v[38:39]
	v_or_b32_e32 v38, 2, v36
	v_ashrrev_i32_e32 v39, 31, v38
	v_lshlrev_b64 v[38:39], 12, v[38:39]
	s_waitcnt vmcnt(0)
	v_mul_f32_e32 v34, 0x3fd744fd, v34
	v_fmac_f32_e32 v34, v44, v62
	global_store_dword v[56:57], v34, off offset:128
	global_load_dword v34, v[58:59], off offset:128
	s_waitcnt vmcnt(0)
	v_mul_f32_e32 v34, 0x3fd744fd, v34
	v_fmac_f32_e32 v34, v45, v62
	global_store_dword v[58:59], v34, off offset:128
	global_load_dword v34, v[60:61], off offset:128
	v_lshl_add_u64 v[44:45], s[92:93], 0, v[38:39]
	v_or_b32_e32 v38, 3, v36
	v_ashrrev_i32_e32 v39, 31, v38
	v_lshlrev_b64 v[38:39], 12, v[38:39]
	s_waitcnt vmcnt(0)
	v_mul_f32_e32 v34, 0x3fd744fd, v34
	v_fmac_f32_e32 v34, v46, v62
	global_store_dword v[60:61], v34, off offset:128
	global_load_dword v34, v[74:75], off offset:128
	s_waitcnt vmcnt(0)
	v_mul_f32_e32 v34, 0x3fd744fd, v34
	v_fmac_f32_e32 v34, v47, v62
	global_store_dword v[74:75], v34, off offset:128
	global_load_dword v34, v[50:51], off offset:128
	v_lshl_add_u64 v[46:47], s[92:93], 0, v[38:39]
	v_or_b32_e32 v38, 8, v36
	v_ashrrev_i32_e32 v39, 31, v38
	v_lshlrev_b64 v[38:39], 12, v[38:39]
	s_waitcnt vmcnt(0)
	v_mul_f32_e32 v34, 0x3fd744fd, v34
	v_fmac_f32_e32 v34, v48, v62
	global_store_dword v[50:51], v34, off offset:128
	global_load_dword v34, v[52:53], off offset:128
	v_lshl_add_u64 v[50:51], s[92:93], 0, v[38:39]
	v_or_b32_e32 v38, 9, v36
	v_ashrrev_i32_e32 v39, 31, v38
	v_lshlrev_b64 v[38:39], 12, v[38:39]
	s_waitcnt vmcnt(0)
	v_mul_f32_e32 v34, 0x3fd744fd, v34
	v_fmac_f32_e32 v34, v49, v62
	global_store_dword v[52:53], v34, off offset:128
	v_lshl_add_u64 v[52:53], s[92:93], 0, v[38:39]
	v_or_b32_e32 v38, 10, v36
	v_ashrrev_i32_e32 v39, 31, v38
	v_lshlrev_b64 v[38:39], 12, v[38:39]
	v_lshl_add_u64 v[54:55], s[92:93], 0, v[38:39]
	v_or_b32_e32 v38, 11, v36
	v_ashrrev_i32_e32 v39, 31, v38
	v_lshlrev_b64 v[38:39], 12, v[38:39]
	v_lshl_add_u64 v[56:57], s[92:93], 0, v[38:39]
	v_or_b32_e32 v38, 16, v36
	v_ashrrev_i32_e32 v39, 31, v38
	v_lshlrev_b64 v[38:39], 12, v[38:39]
	v_lshl_add_u64 v[58:59], s[92:93], 0, v[38:39]
	v_or_b32_e32 v38, 17, v36
	v_ashrrev_i32_e32 v39, 31, v38
	v_lshlrev_b64 v[38:39], 12, v[38:39]
	v_lshl_add_u64 v[60:61], s[92:93], 0, v[38:39]
	v_or_b32_e32 v38, 18, v36
	v_ashrrev_i32_e32 v39, 31, v38
	v_lshlrev_b64 v[38:39], 12, v[38:39]
	v_lshl_add_u64 v[62:63], s[92:93], 0, v[38:39]
	v_or_b32_e32 v38, 19, v36
	v_ashrrev_i32_e32 v39, 31, v38
	v_lshlrev_b64 v[38:39], 12, v[38:39]
	v_lshl_add_u64 v[64:65], s[92:93], 0, v[38:39]
	v_or_b32_e32 v38, 24, v36
	v_cndmask_b32_e32 v34, 0, v105, vcc
	v_ashrrev_i32_e32 v39, 31, v38
	v_add_u32_e32 v34, s40, v34
	v_lshlrev_b64 v[38:39], 12, v[38:39]
	v_mad_u64_u32 v[34:35], s[4:5], v34, s63, v[68:69]
	v_lshl_add_u64 v[68:69], s[92:93], 0, v[38:39]
	v_or_b32_e32 v38, 25, v36
	v_ashrrev_i32_e32 v39, 31, v38
	v_lshlrev_b64 v[38:39], 12, v[38:39]
	v_lshl_add_u64 v[70:71], s[92:93], 0, v[38:39]
	v_or_b32_e32 v38, 26, v36
	v_ashrrev_i32_e32 v39, 31, v38
	v_or_b32_e32 v36, 27, v36
	v_lshlrev_b64 v[38:39], 12, v[38:39]
	v_ashrrev_i32_e32 v37, 31, v36
	v_lshl_add_u64 v[72:73], s[92:93], 0, v[38:39]
	v_lshlrev_b64 v[36:37], 12, v[36:37]
	v_lshl_add_u64 v[38:39], v[34:35], 0, v[66:67]
	v_lshl_add_u64 v[34:35], v[40:41], 0, v[66:67]
	v_lshl_add_u64 v[48:49], s[92:93], 0, v[36:37]
	global_load_dword v74, v[38:39], off
	global_load_dword v36, v[34:35], off
	v_lshl_add_u64 v[40:41], v[44:45], 0, v[66:67]
	v_lshl_add_u64 v[44:45], v[52:53], 0, v[66:67]
	v_lshl_add_u64 v[52:53], v[64:65], 0, v[66:67]
	s_waitcnt vmcnt(0)
	v_mul_f32_e32 v36, 0x3fd744fd, v36
	v_fmac_f32_e32 v36, v18, v74
	global_store_dword v[34:35], v36, off
	v_lshl_add_u64 v[36:37], v[42:43], 0, v[66:67]
	global_load_dword v18, v[36:37], off
	v_lshl_add_u64 v[42:43], v[46:47], 0, v[66:67]
	v_lshl_add_u64 v[46:47], v[56:57], 0, v[66:67]
	s_waitcnt vmcnt(0)
	v_mul_f32_e32 v18, 0x3fd744fd, v18
	v_fmac_f32_e32 v18, v19, v74
	global_store_dword v[36:37], v18, off
	global_load_dword v18, v[40:41], off
	s_waitcnt vmcnt(0)
	v_mul_f32_e32 v18, 0x3fd744fd, v18
	v_fmac_f32_e32 v18, v20, v74
	global_store_dword v[40:41], v18, off
	global_load_dword v18, v[42:43], off
	s_waitcnt vmcnt(0)
	v_mul_f32_e32 v18, 0x3fd744fd, v18
	v_fmac_f32_e32 v18, v21, v74
	v_lshl_add_u64 v[20:21], v[50:51], 0, v[66:67]
	global_store_dword v[42:43], v18, off
	global_load_dword v18, v[20:21], off
	v_lshl_add_u64 v[50:51], v[60:61], 0, v[66:67]
	s_waitcnt vmcnt(0)
	v_mul_f32_e32 v18, 0x3fd744fd, v18
	v_fmac_f32_e32 v18, v22, v74
	global_store_dword v[20:21], v18, off
	global_load_dword v18, v[44:45], off
	s_waitcnt vmcnt(0)
	v_mul_f32_e32 v18, 0x3fd744fd, v18
	v_fmac_f32_e32 v18, v23, v74
	v_lshl_add_u64 v[22:23], v[54:55], 0, v[66:67]
	global_store_dword v[44:45], v18, off
	global_load_dword v18, v[22:23], off
	v_lshl_add_u64 v[54:55], v[70:71], 0, v[66:67]
	s_waitcnt vmcnt(0)
	v_mul_f32_e32 v18, 0x3fd744fd, v18
	v_fmac_f32_e32 v18, v24, v74
	global_store_dword v[22:23], v18, off
	global_load_dword v18, v[46:47], off
	s_waitcnt vmcnt(0)
	v_mul_f32_e32 v18, 0x3fd744fd, v18
	v_fmac_f32_e32 v18, v25, v74
	v_lshl_add_u64 v[24:25], v[58:59], 0, v[66:67]
	global_store_dword v[46:47], v18, off
	global_load_dword v18, v[24:25], off
	s_waitcnt vmcnt(0)
	v_mul_f32_e32 v18, 0x3fd744fd, v18
	v_fmac_f32_e32 v18, v26, v74
	global_store_dword v[24:25], v18, off
	global_load_dword v18, v[50:51], off
	s_waitcnt vmcnt(0)
	v_mul_f32_e32 v18, 0x3fd744fd, v18
	v_fmac_f32_e32 v18, v27, v74
	v_lshl_add_u64 v[26:27], v[62:63], 0, v[66:67]
	global_store_dword v[50:51], v18, off
	global_load_dword v18, v[26:27], off
	s_waitcnt vmcnt(0)
	v_mul_f32_e32 v18, 0x3fd744fd, v18
	v_fmac_f32_e32 v18, v28, v74
	global_store_dword v[26:27], v18, off
	global_load_dword v18, v[52:53], off
	s_waitcnt vmcnt(0)
	v_mul_f32_e32 v18, 0x3fd744fd, v18
	v_fmac_f32_e32 v18, v29, v74
	v_lshl_add_u64 v[28:29], v[68:69], 0, v[66:67]
	global_store_dword v[52:53], v18, off
	global_load_dword v18, v[28:29], off
	s_waitcnt vmcnt(0)
	v_mul_f32_e32 v18, 0x3fd744fd, v18
	v_fmac_f32_e32 v18, v30, v74
	global_store_dword v[28:29], v18, off
	global_load_dword v18, v[54:55], off
	s_waitcnt vmcnt(0)
	v_mul_f32_e32 v18, 0x3fd744fd, v18
	v_fmac_f32_e32 v18, v31, v74
	v_lshl_add_u64 v[30:31], v[72:73], 0, v[66:67]
	global_store_dword v[54:55], v18, off
	global_load_dword v18, v[30:31], off
	s_waitcnt vmcnt(0)
	v_mul_f32_e32 v18, 0x3fd744fd, v18
	v_fmac_f32_e32 v18, v32, v74
	global_store_dword v[30:31], v18, off
	v_lshl_add_u64 v[18:19], v[48:49], 0, v[66:67]
	global_load_dword v32, v[18:19], off
	s_waitcnt vmcnt(0)
	v_mul_f32_e32 v32, 0x3fd744fd, v32
	v_fmac_f32_e32 v32, v33, v74
	global_store_dword v[18:19], v32, off
	global_load_dword v32, v[38:39], off offset:128
	s_nop 0
	global_load_dword v33, v[34:35], off offset:128
	s_waitcnt vmcnt(0)
	v_mul_f32_e32 v33, 0x3fd744fd, v33
	v_fmac_f32_e32 v33, v2, v32
	global_load_dword v2, v[36:37], off offset:128
	s_waitcnt vmcnt(0)
	v_mul_f32_e32 v2, 0x3fd744fd, v2
	v_fmac_f32_e32 v2, v3, v32
	global_store_dword v[36:37], v2, off offset:128
	global_load_dword v2, v[40:41], off offset:128
	s_waitcnt vmcnt(0)
	v_mul_f32_e32 v2, 0x3fd744fd, v2
	v_fmac_f32_e32 v2, v4, v32
	global_store_dword v[40:41], v2, off offset:128
	global_load_dword v2, v[42:43], off offset:128
	s_waitcnt vmcnt(0)
	v_mul_f32_e32 v2, 0x3fd744fd, v2
	v_fmac_f32_e32 v2, v5, v32
	global_store_dword v[42:43], v2, off offset:128
	global_load_dword v2, v[20:21], off offset:128
	s_waitcnt vmcnt(0)
	v_mul_f32_e32 v2, 0x3fd744fd, v2
	v_fmac_f32_e32 v2, v6, v32
	global_store_dword v[20:21], v2, off offset:128
	global_load_dword v2, v[44:45], off offset:128
	s_waitcnt vmcnt(0)
	v_mul_f32_e32 v2, 0x3fd744fd, v2
	v_fmac_f32_e32 v2, v7, v32
	global_store_dword v[44:45], v2, off offset:128
	global_load_dword v2, v[22:23], off offset:128
	s_waitcnt vmcnt(0)
	v_mul_f32_e32 v2, 0x3fd744fd, v2
	v_fmac_f32_e32 v2, v8, v32
	global_store_dword v[22:23], v2, off offset:128
	global_load_dword v2, v[46:47], off offset:128
	s_waitcnt vmcnt(0)
	v_mul_f32_e32 v2, 0x3fd744fd, v2
	v_fmac_f32_e32 v2, v9, v32
	global_store_dword v[46:47], v2, off offset:128
	global_load_dword v2, v[24:25], off offset:128
	s_waitcnt vmcnt(0)
	v_mul_f32_e32 v2, 0x3fd744fd, v2
	v_fmac_f32_e32 v2, v10, v32
	global_store_dword v[24:25], v2, off offset:128
	global_load_dword v2, v[50:51], off offset:128
	s_waitcnt vmcnt(0)
	v_mul_f32_e32 v2, 0x3fd744fd, v2
	v_fmac_f32_e32 v2, v11, v32
	global_store_dword v[50:51], v2, off offset:128
	global_load_dword v2, v[26:27], off offset:128
	s_waitcnt vmcnt(0)
	v_mul_f32_e32 v2, 0x3fd744fd, v2
	v_fmac_f32_e32 v2, v12, v32
	global_store_dword v[26:27], v2, off offset:128
	global_load_dword v2, v[52:53], off offset:128
	s_waitcnt vmcnt(0)
	v_mul_f32_e32 v2, 0x3fd744fd, v2
	v_fmac_f32_e32 v2, v13, v32
	global_store_dword v[52:53], v2, off offset:128
	global_load_dword v2, v[28:29], off offset:128
	s_waitcnt vmcnt(0)
	v_mul_f32_e32 v2, 0x3fd744fd, v2
	v_fmac_f32_e32 v2, v14, v32
	global_store_dword v[28:29], v2, off offset:128
	global_load_dword v2, v[54:55], off offset:128
	s_waitcnt vmcnt(0)
	v_mul_f32_e32 v2, 0x3fd744fd, v2
	v_fmac_f32_e32 v2, v15, v32
	global_store_dword v[54:55], v2, off offset:128
	global_load_dword v2, v[30:31], off offset:128
	s_waitcnt vmcnt(0)
	v_mul_f32_e32 v2, 0x3fd744fd, v2
	v_fmac_f32_e32 v2, v16, v32
	global_store_dword v[30:31], v2, off offset:128
	global_load_dword v2, v[18:19], off offset:128
	s_waitcnt vmcnt(0)
	v_mul_f32_e32 v2, 0x3fd744fd, v2
	v_fmac_f32_e32 v2, v17, v32
	global_store_dword v[34:35], v33, off offset:128
	global_store_dword v[18:19], v2, off offset:128
	s_cmp_gt_u32 s33, 47
	s_cbranch_scc1 .LBB0_642
	s_barrier
	s_and_saveexec_b64 s[4:5], s[14:15]
	s_xor_b64 s[4:5], exec, s[4:5]
	s_cbranch_execz .LBB0_628
	s_mov_b64 s[8:9], exec
	v_mbcnt_lo_u32_b32 v2, s8, 0
	v_mbcnt_hi_u32_b32 v2, s9, v2
	v_cmp_eq_u32_e32 vcc, 0, v2
	s_and_saveexec_b64 s[6:7], vcc
	s_cbranch_execz .LBB0_627
	s_bcnt1_i32_b64 s8, s[8:9]
	v_mov_b32_e32 v3, s8
	global_atomic_add v3, v1, v3, s[2:3] sc0
	s_branch .LBB0_627

.LBB0_762:
	v_or_b32_e32 v66, s4, v135
	v_add_u32_e32 v68, s2, v149
	v_ashrrev_i32_e32 v69, 31, v68
	v_or_b32_e32 v72, 1, v68
	v_ashrrev_i32_e32 v67, 31, v66
	v_lshlrev_b64 v[70:71], 11, v[68:69]
	v_ashrrev_i32_e32 v73, 31, v72
	v_or_b32_e32 v74, 2, v68
	v_lshl_add_u64 v[66:67], v[66:67], 1, s[34:35]
	v_lshlrev_b64 v[72:73], 11, v[72:73]
	v_ashrrev_i32_e32 v75, 31, v74
	v_or_b32_e32 v76, 3, v68
	v_cvt_pk_bf16_f32 v50, v50, s0
	v_lshl_add_u64 v[70:71], v[66:67], 0, v[70:71]
	v_cvt_pk_bf16_f32 v34, v34, s0
	v_lshlrev_b64 v[74:75], 11, v[74:75]
	v_ashrrev_i32_e32 v77, 31, v76
	v_or_b32_e32 v78, 8, v68
	global_store_short v[70:71], v50, off
	v_cvt_pk_bf16_f32 v69, v51, s0
	v_lshl_add_u64 v[50:51], v[66:67], 0, v[72:73]
	global_store_short v[70:71], v34, off offset:64
	v_cvt_pk_bf16_f32 v34, v35, s0
	v_lshlrev_b64 v[76:77], 11, v[76:77]
	v_ashrrev_i32_e32 v79, 31, v78
	v_or_b32_e32 v80, 9, v68
	v_cvt_pk_bf16_f32 v52, v52, s0
	v_lshl_add_u64 v[72:73], v[66:67], 0, v[74:75]
	global_store_short v[50:51], v34, off offset:64
	v_cvt_pk_bf16_f32 v34, v36, s0
	v_lshlrev_b64 v[78:79], 11, v[78:79]
	v_ashrrev_i32_e32 v81, 31, v80
	s_waitcnt vmcnt(10)
	v_or_b32_e32 v82, 10, v68
	global_store_short v[50:51], v69, off
	global_store_short v[72:73], v52, off
	v_cvt_pk_bf16_f32 v69, v53, s0
	v_lshl_add_u64 v[52:53], v[66:67], 0, v[76:77]
	global_store_short v[72:73], v34, off offset:64
	v_cvt_pk_bf16_f32 v34, v37, s0
	v_lshlrev_b64 v[80:81], 11, v[80:81]
	v_ashrrev_i32_e32 v83, 31, v82
	v_or_b32_e32 v84, 11, v68
	v_cvt_pk_bf16_f32 v54, v54, s0
	v_lshl_add_u64 v[74:75], v[66:67], 0, v[78:79]
	global_store_short v[52:53], v34, off offset:64
	v_cvt_pk_bf16_f32 v34, v38, s0
	v_lshlrev_b64 v[82:83], 11, v[82:83]
	v_ashrrev_i32_e32 v85, 31, v84
	s_waitcnt vmcnt(13)
	v_or_b32_e32 v86, 16, v68
	global_store_short v[52:53], v69, off
	global_store_short v[74:75], v54, off
	v_cvt_pk_bf16_f32 v69, v55, s0
	v_lshl_add_u64 v[54:55], v[66:67], 0, v[80:81]
	global_store_short v[74:75], v34, off offset:64
	v_cvt_pk_bf16_f32 v34, v39, s0
	v_lshlrev_b64 v[84:85], 11, v[84:85]
	v_ashrrev_i32_e32 v87, 31, v86
	v_or_b32_e32 v88, 17, v68
	v_cvt_pk_bf16_f32 v56, v56, s0
	v_lshl_add_u64 v[76:77], v[66:67], 0, v[82:83]
	global_store_short v[54:55], v34, off offset:64
	v_cvt_pk_bf16_f32 v34, v40, s0
	v_lshlrev_b64 v[86:87], 11, v[86:87]
	v_ashrrev_i32_e32 v89, 31, v88
	v_or_b32_e32 v90, 18, v68
	global_store_short v[54:55], v69, off
	global_store_short v[76:77], v56, off
	v_cvt_pk_bf16_f32 v69, v57, s0
	v_lshl_add_u64 v[56:57], v[66:67], 0, v[84:85]
	global_store_short v[76:77], v34, off offset:64
	v_cvt_pk_bf16_f32 v34, v41, s0
	v_lshlrev_b64 v[88:89], 11, v[88:89]
	v_ashrrev_i32_e32 v91, 31, v90
	v_or_b32_e32 v92, 19, v68
	v_cvt_pk_bf16_f32 v58, v58, s0
	v_lshl_add_u64 v[78:79], v[66:67], 0, v[86:87]
	global_store_short v[56:57], v34, off offset:64
	v_cvt_pk_bf16_f32 v34, v42, s0
	v_lshlrev_b64 v[90:91], 11, v[90:91]
	v_ashrrev_i32_e32 v93, 31, v92
	s_waitcnt vmcnt(20)
	v_or_b32_e32 v94, 24, v68
	global_store_short v[56:57], v69, off
	global_store_short v[78:79], v58, off
	v_cvt_pk_bf16_f32 v69, v59, s0
	v_lshl_add_u64 v[58:59], v[66:67], 0, v[88:89]
	global_store_short v[78:79], v34, off offset:64
	v_cvt_pk_bf16_f32 v34, v43, s0
	v_lshlrev_b64 v[92:93], 11, v[92:93]
	v_ashrrev_i32_e32 v95, 31, v94
	v_or_b32_e32 v96, 25, v68
	v_cvt_pk_bf16_f32 v60, v60, s0
	v_lshl_add_u64 v[80:81], v[66:67], 0, v[90:91]
	global_store_short v[58:59], v34, off offset:64
	v_cvt_pk_bf16_f32 v34, v44, s0
	v_lshlrev_b64 v[94:95], 11, v[94:95]
	v_ashrrev_i32_e32 v97, 31, v96
	s_waitcnt vmcnt(23)
	v_or_b32_e32 v98, 26, v68
	global_store_short v[58:59], v69, off
	global_store_short v[80:81], v60, off
	v_cvt_pk_bf16_f32 v69, v61, s0
	v_lshl_add_u64 v[60:61], v[66:67], 0, v[92:93]
	global_store_short v[80:81], v34, off offset:64
	v_cvt_pk_bf16_f32 v34, v45, s0
	v_lshlrev_b64 v[96:97], 11, v[96:97]
	v_ashrrev_i32_e32 v99, 31, v98
	v_or_b32_e32 v100, 27, v68
	v_cvt_pk_bf16_f32 v62, v62, s0
	v_lshl_add_u64 v[82:83], v[66:67], 0, v[94:95]
	global_store_short v[60:61], v34, off offset:64
	v_cvt_pk_bf16_f32 v34, v46, s0
	v_lshlrev_b64 v[98:99], 11, v[98:99]
	v_ashrrev_i32_e32 v101, 31, v100
	global_store_short v[60:61], v69, off
	global_store_short v[82:83], v62, off
	v_cvt_pk_bf16_f32 v69, v63, s0
	v_lshl_add_u64 v[62:63], v[66:67], 0, v[96:97]
	global_store_short v[82:83], v34, off offset:64
	v_cvt_pk_bf16_f32 v34, v47, s0
	v_lshlrev_b64 v[100:101], 11, v[100:101]
	v_cvt_pk_bf16_f32 v64, v64, s0
	v_lshl_add_u64 v[84:85], v[66:67], 0, v[98:99]
	global_store_short v[62:63], v34, off offset:64
	v_cvt_pk_bf16_f32 v34, v48, s0
	global_store_short v[62:63], v69, off
	global_store_short v[84:85], v64, off
	v_cvt_pk_bf16_f32 v69, v65, s0
	v_lshl_add_u64 v[64:65], v[66:67], 0, v[100:101]
	global_store_short v[84:85], v34, off offset:64
	v_cvt_pk_bf16_f32 v34, v49, s0
	global_store_short v[64:65], v34, off offset:64
	v_or_b32_e32 v34, 32, v68
	v_ashrrev_i32_e32 v35, 31, v34
	v_or_b32_e32 v36, 33, v68
	v_lshlrev_b64 v[34:35], 11, v[34:35]
	v_ashrrev_i32_e32 v37, 31, v36
	v_or_b32_e32 v38, 34, v68
	v_lshlrev_b64 v[36:37], 11, v[36:37]
	v_ashrrev_i32_e32 v39, 31, v38
	v_or_b32_e32 v40, 35, v68
	v_cvt_pk_bf16_f32 v18, v18, s0
	v_lshl_add_u64 v[34:35], v[66:67], 0, v[34:35]
	v_cvt_pk_bf16_f32 v2, v2, s0
	global_store_short v[64:65], v69, off
	v_lshlrev_b64 v[38:39], 11, v[38:39]
	v_ashrrev_i32_e32 v41, 31, v40
	v_or_b32_e32 v42, 40, v68
	v_or_b32_e32 v44, 41, v68
	v_or_b32_e32 v46, 42, v68
	v_or_b32_e32 v48, 43, v68
	v_or_b32_e32 v50, 48, v68
	v_or_b32_e32 v52, 49, v68
	v_or_b32_e32 v54, 50, v68
	v_or_b32_e32 v56, 51, v68
	v_or_b32_e32 v58, 56, v68
	v_or_b32_e32 v60, 57, v68
	v_or_b32_e32 v62, 58, v68
	v_or_b32_e32 v64, 59, v68
	global_store_short v[34:35], v18, off
	v_cvt_pk_bf16_f32 v68, v19, s0
	v_lshl_add_u64 v[18:19], v[66:67], 0, v[36:37]
	global_store_short v[34:35], v2, off offset:64
	v_cvt_pk_bf16_f32 v2, v3, s0
	v_lshlrev_b64 v[40:41], 11, v[40:41]
	v_ashrrev_i32_e32 v43, 31, v42
	v_cvt_pk_bf16_f32 v20, v20, s0
	v_lshl_add_u64 v[36:37], v[66:67], 0, v[38:39]
	global_store_short v[18:19], v2, off offset:64
	v_cvt_pk_bf16_f32 v2, v4, s0
	v_lshlrev_b64 v[42:43], 11, v[42:43]
	v_ashrrev_i32_e32 v45, 31, v44
	global_store_short v[36:37], v20, off
	v_cvt_pk_bf16_f32 v38, v21, s0
	v_lshl_add_u64 v[20:21], v[66:67], 0, v[40:41]
	global_store_short v[36:37], v2, off offset:64
	v_cvt_pk_bf16_f32 v2, v5, s0
	v_lshlrev_b64 v[44:45], 11, v[44:45]
	v_ashrrev_i32_e32 v47, 31, v46
	global_store_short v[20:21], v38, off
	v_cvt_pk_bf16_f32 v22, v22, s0
	v_lshl_add_u64 v[38:39], v[66:67], 0, v[42:43]
	global_store_short v[20:21], v2, off offset:64
	v_cvt_pk_bf16_f32 v2, v6, s0
	v_lshlrev_b64 v[46:47], 11, v[46:47]
	v_ashrrev_i32_e32 v49, 31, v48
	global_store_short v[38:39], v22, off
	v_cvt_pk_bf16_f32 v40, v23, s0
	v_lshl_add_u64 v[22:23], v[66:67], 0, v[44:45]
	global_store_short v[38:39], v2, off offset:64
	v_cvt_pk_bf16_f32 v2, v7, s0
	v_lshlrev_b64 v[48:49], 11, v[48:49]
	v_ashrrev_i32_e32 v51, 31, v50
	global_store_short v[22:23], v40, off
	v_cvt_pk_bf16_f32 v24, v24, s0
	v_lshl_add_u64 v[40:41], v[66:67], 0, v[46:47]
	global_store_short v[22:23], v2, off offset:64
	v_cvt_pk_bf16_f32 v2, v8, s0
	v_lshlrev_b64 v[50:51], 11, v[50:51]
	v_ashrrev_i32_e32 v53, 31, v52
	global_store_short v[40:41], v24, off
	v_cvt_pk_bf16_f32 v42, v25, s0
	v_lshl_add_u64 v[24:25], v[66:67], 0, v[48:49]
	global_store_short v[40:41], v2, off offset:64
	v_cvt_pk_bf16_f32 v2, v9, s0
	v_lshlrev_b64 v[52:53], 11, v[52:53]
	v_ashrrev_i32_e32 v55, 31, v54
	global_store_short v[24:25], v42, off
	v_cvt_pk_bf16_f32 v26, v26, s0
	v_lshl_add_u64 v[42:43], v[66:67], 0, v[50:51]
	global_store_short v[24:25], v2, off offset:64
	v_cvt_pk_bf16_f32 v2, v10, s0
	v_lshlrev_b64 v[54:55], 11, v[54:55]
	v_ashrrev_i32_e32 v57, 31, v56
	global_store_short v[42:43], v26, off
	v_cvt_pk_bf16_f32 v44, v27, s0
	v_lshl_add_u64 v[26:27], v[66:67], 0, v[52:53]
	global_store_short v[42:43], v2, off offset:64
	v_cvt_pk_bf16_f32 v2, v11, s0
	v_lshlrev_b64 v[56:57], 11, v[56:57]
	v_ashrrev_i32_e32 v59, 31, v58
	global_store_short v[26:27], v44, off
	v_cvt_pk_bf16_f32 v28, v28, s0
	v_lshl_add_u64 v[44:45], v[66:67], 0, v[54:55]
	global_store_short v[26:27], v2, off offset:64
	v_cvt_pk_bf16_f32 v2, v12, s0
	v_lshlrev_b64 v[58:59], 11, v[58:59]
	v_ashrrev_i32_e32 v61, 31, v60
	global_store_short v[44:45], v28, off
	v_cvt_pk_bf16_f32 v46, v29, s0
	v_lshl_add_u64 v[28:29], v[66:67], 0, v[56:57]
	global_store_short v[44:45], v2, off offset:64
	v_cvt_pk_bf16_f32 v2, v13, s0
	v_lshlrev_b64 v[60:61], 11, v[60:61]
	v_ashrrev_i32_e32 v63, 31, v62
	global_store_short v[28:29], v46, off
	v_cvt_pk_bf16_f32 v30, v30, s0
	v_lshl_add_u64 v[46:47], v[66:67], 0, v[58:59]
	global_store_short v[28:29], v2, off offset:64
	v_cvt_pk_bf16_f32 v2, v14, s0
	v_lshlrev_b64 v[62:63], 11, v[62:63]
	v_ashrrev_i32_e32 v65, 31, v64
	global_store_short v[46:47], v30, off
	v_cvt_pk_bf16_f32 v48, v31, s0
	v_lshl_add_u64 v[30:31], v[66:67], 0, v[60:61]
	global_store_short v[46:47], v2, off offset:64
	v_cvt_pk_bf16_f32 v2, v15, s0
	v_lshlrev_b64 v[64:65], 11, v[64:65]
	global_store_short v[30:31], v48, off
	v_cvt_pk_bf16_f32 v32, v32, s0
	v_lshl_add_u64 v[48:49], v[66:67], 0, v[62:63]
	global_store_short v[30:31], v2, off offset:64
	v_cvt_pk_bf16_f32 v2, v16, s0
	global_store_short v[48:49], v32, off
	v_cvt_pk_bf16_f32 v50, v33, s0
	v_lshl_add_u64 v[32:33], v[66:67], 0, v[64:65]
	global_store_short v[48:49], v2, off offset:64
	v_cvt_pk_bf16_f32 v2, v17, s0
	global_store_short v[18:19], v68, off
	global_store_short v[32:33], v50, off
	global_store_short v[32:33], v2, off offset:64
	s_cmp_gt_u32 s33, 47
	s_cbranch_scc1 .LBB0_765
	s_waitcnt vmcnt(63) expcnt(7) lgkmcnt(15)
	s_barrier
	s_and_saveexec_b64 s[2:3], s[14:15]
	s_xor_b64 s[2:3], exec, s[2:3]
	s_cbranch_execz .LBB0_751
	s_mov_b64 s[6:7], exec
	v_mbcnt_lo_u32_b32 v2, s6, 0
	v_mbcnt_hi_u32_b32 v2, s7, v2
	v_cmp_eq_u32_e32 vcc, 0, v2
	s_and_saveexec_b64 s[4:5], vcc
	s_cbranch_execz .LBB0_750
	s_bcnt1_i32_b64 s6, s[6:7]
	v_mov_b32_e32 v3, s6
	global_atomic_add v3, v1, v3, s[0:1] sc0
	s_branch .LBB0_750

.LBB0_867:
	s_waitcnt lgkmcnt(14)
	ds_read_b32 v4, v3
	ds_read_b32 v5, v2
	s_waitcnt lgkmcnt(1)
	v_and_b32_e32 v6, 0xffffff80, v4
	s_waitcnt lgkmcnt(0)
	v_and_b32_e32 v7, 0xffffff80, v5
	v_add_f32_e32 v6, v6, v7
	v_cndmask_b32_e64 v6, v212, v6, s[4:5]
	v_ashrrev_i32_e32 v7, 31, v6
	v_or_b32_e32 v7, 0x80000000, v7
	v_xor_b32_e32 v7, v7, v6
	s_mov_b32 s0, 0
	s_or_b32 s1, s0, 0x80000000
	v_cmp_le_u32_e64 s[42:43], s1, v7
	s_bcnt1_i32_b64 s41, s[42:43]
	s_cmp_gt_u32 s41, 15
	s_cselect_b32 s0, s1, s0
	s_or_b32 s1, s0, 0x40000000
	v_cmp_le_u32_e64 s[42:43], s1, v7
	s_bcnt1_i32_b64 s41, s[42:43]
	s_cmp_gt_u32 s41, 15
	s_cselect_b32 s0, s1, s0
	s_or_b32 s1, s0, 0x20000000
	v_cmp_le_u32_e64 s[42:43], s1, v7
	s_bcnt1_i32_b64 s41, s[42:43]
	s_cmp_gt_u32 s41, 15
	s_cselect_b32 s0, s1, s0
	s_or_b32 s1, s0, 0x10000000
	v_cmp_le_u32_e64 s[42:43], s1, v7
	s_bcnt1_i32_b64 s41, s[42:43]
	s_cmp_gt_u32 s41, 15
	s_cselect_b32 s0, s1, s0
	s_or_b32 s1, s0, 0x8000000
	v_cmp_le_u32_e64 s[42:43], s1, v7
	s_bcnt1_i32_b64 s41, s[42:43]
	s_cmp_gt_u32 s41, 15
	s_cselect_b32 s0, s1, s0
	s_or_b32 s1, s0, 0x4000000
	v_cmp_le_u32_e64 s[42:43], s1, v7
	s_bcnt1_i32_b64 s41, s[42:43]
	s_cmp_gt_u32 s41, 15
	s_cselect_b32 s0, s1, s0
	s_or_b32 s1, s0, 0x2000000
	v_cmp_le_u32_e64 s[42:43], s1, v7
	s_bcnt1_i32_b64 s41, s[42:43]
	s_cmp_gt_u32 s41, 15
	s_cselect_b32 s0, s1, s0
	s_or_b32 s1, s0, 0x1000000
	v_cmp_le_u32_e64 s[42:43], s1, v7
	s_bcnt1_i32_b64 s41, s[42:43]
	s_cmp_gt_u32 s41, 15
	s_cselect_b32 s0, s1, s0
	s_or_b32 s1, s0, 0x800000
	v_cmp_le_u32_e64 s[42:43], s1, v7
	s_bcnt1_i32_b64 s41, s[42:43]
	s_cmp_gt_u32 s41, 15
	s_cselect_b32 s0, s1, s0
	s_or_b32 s1, s0, 0x400000
	v_cmp_le_u32_e64 s[42:43], s1, v7
	s_bcnt1_i32_b64 s41, s[42:43]
	s_cmp_gt_u32 s41, 15
	s_cselect_b32 s0, s1, s0
	s_or_b32 s1, s0, 0x200000
	v_cmp_le_u32_e64 s[42:43], s1, v7
	s_bcnt1_i32_b64 s41, s[42:43]
	s_cmp_gt_u32 s41, 15
	s_cselect_b32 s0, s1, s0
	s_or_b32 s1, s0, 0x100000
	v_cmp_le_u32_e64 s[42:43], s1, v7
	s_bcnt1_i32_b64 s41, s[42:43]
	s_cmp_gt_u32 s41, 15
	s_cselect_b32 s0, s1, s0
	s_or_b32 s1, s0, 0x80000
	v_cmp_le_u32_e64 s[42:43], s1, v7
	s_bcnt1_i32_b64 s41, s[42:43]
	s_cmp_gt_u32 s41, 15
	s_cselect_b32 s0, s1, s0
	s_or_b32 s1, s0, 0x40000
	v_cmp_le_u32_e64 s[42:43], s1, v7
	s_bcnt1_i32_b64 s41, s[42:43]
	s_cmp_gt_u32 s41, 15
	s_cselect_b32 s0, s1, s0
	s_or_b32 s1, s0, 0x20000
	v_cmp_le_u32_e64 s[42:43], s1, v7
	s_bcnt1_i32_b64 s41, s[42:43]
	s_cmp_gt_u32 s41, 15
	s_cselect_b32 s0, s1, s0
	s_or_b32 s1, s0, 0x10000
	v_cmp_le_u32_e64 s[42:43], s1, v7
	s_bcnt1_i32_b64 s41, s[42:43]
	s_cmp_gt_u32 s41, 15
	s_cselect_b32 s0, s1, s0
	s_or_b32 s1, s0, 0x8000
	v_cmp_le_u32_e64 s[42:43], s1, v7
	s_bcnt1_i32_b64 s41, s[42:43]
	s_cmp_gt_u32 s41, 15
	s_cselect_b32 s0, s1, s0
	s_or_b32 s1, s0, 0x4000
	v_cmp_le_u32_e64 s[42:43], s1, v7
	s_bcnt1_i32_b64 s41, s[42:43]
	s_cmp_gt_u32 s41, 15
	s_cselect_b32 s0, s1, s0
	s_or_b32 s1, s0, 0x2000
	v_cmp_le_u32_e64 s[42:43], s1, v7
	s_bcnt1_i32_b64 s41, s[42:43]
	s_cmp_gt_u32 s41, 15
	s_cselect_b32 s0, s1, s0
	s_or_b32 s1, s0, 0x1000
	v_cmp_le_u32_e64 s[42:43], s1, v7
	s_bcnt1_i32_b64 s41, s[42:43]
	s_cmp_gt_u32 s41, 15
	s_cselect_b32 s0, s1, s0
	v_cmp_le_u32_e64 s[42:43], s0, v7
	s_bcnt1_i32_b64 s41, s[42:43]
	s_cmp_eq_u32 s41, 16
	s_cbranch_scc1 .Lpeer_thresh_done
	s_or_b32 s1, s0, 0x800
	v_cmp_le_u32_e64 s[42:43], s1, v7
	s_bcnt1_i32_b64 s41, s[42:43]
	s_cmp_gt_u32 s41, 15
	s_cselect_b32 s0, s1, s0
	s_or_b32 s1, s0, 0x400
	v_cmp_le_u32_e64 s[42:43], s1, v7
	s_bcnt1_i32_b64 s41, s[42:43]
	s_cmp_gt_u32 s41, 15
	s_cselect_b32 s0, s1, s0
	s_or_b32 s1, s0, 0x200
	v_cmp_le_u32_e64 s[42:43], s1, v7
	s_bcnt1_i32_b64 s41, s[42:43]
	s_cmp_gt_u32 s41, 15
	s_cselect_b32 s0, s1, s0
	s_or_b32 s1, s0, 0x100
	v_cmp_le_u32_e64 s[42:43], s1, v7
	s_bcnt1_i32_b64 s41, s[42:43]
	s_cmp_gt_u32 s41, 15
	s_cselect_b32 s0, s1, s0
	s_or_b32 s1, s0, 0x80
	v_cmp_le_u32_e64 s[42:43], s1, v7
	s_bcnt1_i32_b64 s41, s[42:43]
	s_cmp_gt_u32 s41, 15
	s_cselect_b32 s0, s1, s0
	s_or_b32 s1, s0, 0x40
	v_cmp_le_u32_e64 s[42:43], s1, v7
	s_bcnt1_i32_b64 s41, s[42:43]
	s_cmp_gt_u32 s41, 15
	s_cselect_b32 s0, s1, s0
	s_or_b32 s1, s0, 0x20
	v_cmp_le_u32_e64 s[42:43], s1, v7
	s_bcnt1_i32_b64 s41, s[42:43]
	s_cmp_gt_u32 s41, 15
	s_cselect_b32 s0, s1, s0
	s_or_b32 s1, s0, 0x10
	v_cmp_le_u32_e64 s[42:43], s1, v7
	s_bcnt1_i32_b64 s41, s[42:43]
	s_cmp_gt_u32 s41, 15
	s_cselect_b32 s0, s1, s0
	s_or_b32 s1, s0, 0x8
	v_cmp_le_u32_e64 s[42:43], s1, v7
	s_bcnt1_i32_b64 s41, s[42:43]
	s_cmp_gt_u32 s41, 15
	s_cselect_b32 s0, s1, s0
	s_or_b32 s1, s0, 0x4
	v_cmp_le_u32_e64 s[42:43], s1, v7
	s_bcnt1_i32_b64 s41, s[42:43]
	s_cmp_gt_u32 s41, 15
	s_cselect_b32 s0, s1, s0
	s_or_b32 s1, s0, 0x2
	v_cmp_le_u32_e64 s[42:43], s1, v7
	s_bcnt1_i32_b64 s41, s[42:43]
	s_cmp_gt_u32 s41, 15
	s_cselect_b32 s0, s1, s0
	s_or_b32 s1, s0, 0x1
	v_cmp_le_u32_e64 s[42:43], s1, v7
	s_bcnt1_i32_b64 s41, s[42:43]
	s_cmp_gt_u32 s41, 15
	s_cselect_b32 s0, s1, s0
.Lpeer_thresh_done:
	v_cmp_le_u32_e32 vcc, s0, v7
	s_and_b64 vcc, s[4:5], vcc
	v_cndmask_b32_e64 v7, 0, 1, vcc
	v_readlane_b32 s0, v6, 0
	s_nop 1
	v_subrev_f32_e32 v6, s0, v6
	v_mul_f32_e32 v6, 0x3fb8aa3b, v6
	v_exp_f32_e32 v6, v6
	v_cmp_ne_u32_e64 s[0:1], 0, v7
	v_cndmask_b32_e32 v6, 0, v6, vcc
	ds_bpermute_b32 v8, v215, v6
	v_mbcnt_lo_u32_b32 v7, s0, 0
	v_mbcnt_hi_u32_b32 v7, s1, v7
	v_cmp_gt_i32_e64 s[0:1], 16, v7
	s_and_b64 s[42:43], vcc, s[0:1]
	s_waitcnt lgkmcnt(0)
	v_add_f32_e32 v8, v6, v8
	ds_bpermute_b32 v9, v214, v8
	s_waitcnt lgkmcnt(0)
	v_add_f32_e32 v8, v8, v9
	v_lshlrev_b32_e32 v5, 7, v5
	v_and_b32_e32 v4, 0x7f, v4
	v_add_f32_dpp v8, v8, v8 row_ror:8 row_mask:0xf bank_mask:0xf
	s_movk_i32 s41, 0x3f80
	v_and_or_b32 v4, v5, s41, v4
	v_mov_b32_dpp v9, v8 row_half_mirror row_mask:0xf bank_mask:0xf
	v_add_u32_e32 v5, s20, v7
	s_nop 0
	v_add_f32_dpp v8, v9, v8 quad_perm:[3,2,1,0] row_mask:0xf bank_mask:0xf
	s_nop 1
	v_add_f32_dpp v8, v8, v8 quad_perm:[2,3,0,1] row_mask:0xf bank_mask:0xf
	s_nop 1
	v_add_f32_dpp v8, v8, v8 quad_perm:[1,0,3,2] row_mask:0xf bank_mask:0xf
	s_and_saveexec_b64 s[0:1], s[42:43]
	s_cbranch_execz .LBB0_866
	v_div_scale_f32 v9, s[42:43], v8, v8, v6
	v_rcp_f32_e32 v10, v9
	s_nop 0
	v_fma_f32 v7, -v9, v10, 1.0
	v_fmac_f32_e32 v10, v7, v10
	v_div_scale_f32 v7, vcc, v6, v8, v6
	v_mul_f32_e32 v11, v7, v10
	v_fma_f32 v12, -v9, v11, v7
	v_fmac_f32_e32 v11, v12, v10
	v_fma_f32 v7, -v9, v11, v7
	v_div_fmas_f32 v7, v7, v10, v11
	v_lshl_add_u32 v5, v5, 2, v131
	v_div_fixup_f32 v6, v7, v8, v6
	ds_write2st64_b32 v5, v4, v6 offset0:12 offset1:14
	s_branch .LBB0_866

.LBB0_870:
	v_add_u32_e32 v0, s1, v199
	ds_read_b128 v[2:5], v0
	ds_read_b128 v[6:9], v0 offset:16
	ds_read_b128 v[14:17], v0 offset:32
	ds_read_b128 v[26:29], v0 offset:48
	s_waitcnt lgkmcnt(3)
	v_readfirstlane_b32 s20, v2
	s_lshl_b64 s[42:43], s[20:21], 11
	v_lshl_add_u64 v[22:23], v[140:141], 0, s[42:43]
	global_load_dwordx4 v[126:129], v[22:23], off
	v_readfirstlane_b32 s20, v3
	s_lshl_b64 s[42:43], s[20:21], 11
	v_lshl_add_u64 v[24:25], v[140:141], 0, s[42:43]
	global_load_dwordx4 v[122:125], v[24:25], off
	v_readfirstlane_b32 s20, v4
	s_lshl_b64 s[42:43], s[20:21], 11
	v_lshl_add_u64 v[20:21], v[140:141], 0, s[42:43]
	global_load_dwordx4 v[118:121], v[20:21], off
	v_readfirstlane_b32 s20, v5
	s_lshl_b64 s[42:43], s[20:21], 11
	s_waitcnt lgkmcnt(2)
	v_readfirstlane_b32 s20, v6
	v_lshl_add_u64 v[18:19], v[140:141], 0, s[42:43]
	s_lshl_b64 s[42:43], s[20:21], 11
	v_readfirstlane_b32 s20, v7
	v_lshl_add_u64 v[10:11], v[140:141], 0, s[42:43]
	s_lshl_b64 s[42:43], s[20:21], 11
	v_readfirstlane_b32 s20, v8
	v_lshl_add_u64 v[2:3], v[140:141], 0, s[42:43]
	s_lshl_b64 s[42:43], s[20:21], 11
	v_readfirstlane_b32 s20, v9
	v_lshl_add_u64 v[4:5], v[140:141], 0, s[42:43]
	s_lshl_b64 s[42:43], s[20:21], 11
	s_waitcnt lgkmcnt(1)
	v_readfirstlane_b32 s20, v14
	v_lshl_add_u64 v[6:7], v[140:141], 0, s[42:43]
	s_lshl_b64 s[42:43], s[20:21], 11
	v_readfirstlane_b32 s20, v15
	global_load_dwordx4 v[114:117], v[18:19], off
	v_lshl_add_u64 v[8:9], v[140:141], 0, s[42:43]
	s_lshl_b64 s[42:43], s[20:21], 11
	v_readfirstlane_b32 s20, v16
	v_lshl_add_u64 v[12:13], v[140:141], 0, s[42:43]
	s_lshl_b64 s[42:43], s[20:21], 11
	v_readfirstlane_b32 s20, v17
	v_lshl_add_u64 v[14:15], v[140:141], 0, s[42:43]
	s_lshl_b64 s[42:43], s[20:21], 11
	s_waitcnt lgkmcnt(0)
	v_readfirstlane_b32 s20, v26
	v_lshl_add_u64 v[16:17], v[140:141], 0, s[42:43]
	s_lshl_b64 s[42:43], s[20:21], 11
	v_readfirstlane_b32 s20, v27
	v_lshl_add_u64 v[188:189], v[140:141], 0, s[42:43]
	s_lshl_b64 s[42:43], s[20:21], 11
	v_readfirstlane_b32 s20, v28
	v_lshl_add_u64 v[190:191], v[140:141], 0, s[42:43]
	s_lshl_b64 s[42:43], s[20:21], 11
	v_readfirstlane_b32 s20, v29
	v_lshl_add_u64 v[192:193], v[140:141], 0, s[42:43]
	s_lshl_b64 s[42:43], s[20:21], 11
	v_lshl_add_u64 v[194:195], v[140:141], 0, s[42:43]
	global_load_dwordx4 v[110:113], v[10:11], off
	global_load_dwordx4 v[90:93], v[12:13], off
	global_load_dwordx4 v[106:109], v[2:3], off
	global_load_dwordx4 v[102:105], v[4:5], off
	global_load_dwordx4 v[98:101], v[6:7], off
	global_load_dwordx4 v[94:97], v[8:9], off
	global_load_dwordx4 v[86:89], v[14:15], off
	global_load_dwordx4 v[82:85], v[16:17], off
	global_load_dwordx4 v[78:81], v[188:189], off
	global_load_dwordx4 v[74:77], v[190:191], off
	global_load_dwordx4 v[70:73], v[192:193], off
	global_load_dwordx4 v[66:69], v[194:195], off
	global_load_dwordx4 v[62:65], v[22:23], off offset:1024
	global_load_dwordx4 v[58:61], v[24:25], off offset:1024
	global_load_dwordx4 v[54:57], v[20:21], off offset:1024
	global_load_dwordx4 v[50:53], v[18:19], off offset:1024
	global_load_dwordx4 v[46:49], v[10:11], off offset:1024
	global_load_dwordx4 v[42:45], v[2:3], off offset:1024
	global_load_dwordx4 v[38:41], v[4:5], off offset:1024
	global_load_dwordx4 v[34:37], v[6:7], off offset:1024
	global_load_dwordx4 v[30:33], v[8:9], off offset:1024
	global_load_dwordx4 v[26:29], v[12:13], off offset:1024
	global_load_dwordx4 v[22:25], v[14:15], off offset:1024
	global_load_dwordx4 v[18:21], v[16:17], off offset:1024
	s_nop 0
	global_load_dwordx4 v[14:17], v[188:189], off offset:1024
	global_load_dwordx4 v[10:13], v[190:191], off offset:1024
	global_load_dwordx4 v[6:9], v[192:193], off offset:1024
	global_load_dwordx4 v[2:5], v[194:195], off offset:1024
	s_waitcnt vmcnt(31)
	v_cvt_pk_f32_fp8_e32 v[188:189], v126
	v_cvt_pk_f32_fp8_sdwa v[190:191], v126 src0_sel:WORD_1
	v_pk_fma_f32 v[188:189], v[188:189], v[154:155], 0 op_sel_hi:[1,1,0]
	s_nop 0
	v_pk_fma_f32 v[188:189], v[190:191], v[156:157], v[188:189]
	v_cvt_pk_f32_fp8_e32 v[190:191], v127
	v_cvt_pk_f32_fp8_sdwa v[126:127], v127 src0_sel:WORD_1
	v_pk_fma_f32 v[188:189], v[190:191], v[158:159], v[188:189]
	s_nop 0
	v_pk_fma_f32 v[126:127], v[126:127], v[162:163], v[188:189]
	v_cvt_pk_f32_fp8_e32 v[188:189], v128
	v_pk_fma_f32 v[126:127], v[188:189], v[164:165], v[126:127]
	v_cvt_pk_f32_fp8_sdwa v[188:189], v128 src0_sel:WORD_1
	v_pk_fma_f32 v[126:127], v[188:189], v[166:167], v[126:127]
	v_cvt_pk_f32_fp8_e32 v[188:189], v129
	v_cvt_pk_f32_fp8_sdwa v[128:129], v129 src0_sel:WORD_1
	v_pk_fma_f32 v[126:127], v[188:189], v[168:169], v[126:127]
	s_nop 0
	v_pk_fma_f32 v[126:127], v[128:129], v[170:171], v[126:127]
	s_waitcnt vmcnt(30)
	v_cvt_pk_f32_fp8_sdwa v[128:129], v122 src0_sel:WORD_1
	v_add_f32_e32 v0, v126, v127
	v_cvt_pk_f32_fp8_e32 v[126:127], v122
	v_pk_fma_f32 v[126:127], v[126:127], v[154:155], 0 op_sel_hi:[1,1,0]
	s_nop 0
	v_pk_fma_f32 v[126:127], v[128:129], v[156:157], v[126:127]
	v_cvt_pk_f32_fp8_e32 v[128:129], v123
	v_cvt_pk_f32_fp8_sdwa v[122:123], v123 src0_sel:WORD_1
	v_pk_fma_f32 v[126:127], v[128:129], v[158:159], v[126:127]
	s_nop 0
	v_pk_fma_f32 v[122:123], v[122:123], v[162:163], v[126:127]
	v_cvt_pk_f32_fp8_e32 v[126:127], v124
	v_pk_fma_f32 v[122:123], v[126:127], v[164:165], v[122:123]
	v_cvt_pk_f32_fp8_sdwa v[126:127], v124 src0_sel:WORD_1
	v_pk_fma_f32 v[122:123], v[126:127], v[166:167], v[122:123]
	v_cvt_pk_f32_fp8_e32 v[126:127], v125
	v_cvt_pk_f32_fp8_sdwa v[124:125], v125 src0_sel:WORD_1
	v_pk_fma_f32 v[122:123], v[126:127], v[168:169], v[122:123]
	s_nop 0
	v_pk_fma_f32 v[122:123], v[124:125], v[170:171], v[122:123]
	s_waitcnt vmcnt(29)
	v_cvt_pk_f32_fp8_sdwa v[124:125], v118 src0_sel:WORD_1
	v_add_f32_e32 v126, v122, v123
	v_cvt_pk_f32_fp8_e32 v[122:123], v118
	v_pk_fma_f32 v[122:123], v[122:123], v[154:155], 0 op_sel_hi:[1,1,0]
	s_nop 0
	v_pk_fma_f32 v[122:123], v[124:125], v[156:157], v[122:123]
	v_cvt_pk_f32_fp8_e32 v[124:125], v119
	v_cvt_pk_f32_fp8_sdwa v[118:119], v119 src0_sel:WORD_1
	v_pk_fma_f32 v[122:123], v[124:125], v[158:159], v[122:123]
	s_nop 0
	v_pk_fma_f32 v[118:119], v[118:119], v[162:163], v[122:123]
	v_cvt_pk_f32_fp8_e32 v[122:123], v120
	v_pk_fma_f32 v[118:119], v[122:123], v[164:165], v[118:119]
	v_cvt_pk_f32_fp8_sdwa v[122:123], v120 src0_sel:WORD_1
	v_pk_fma_f32 v[118:119], v[122:123], v[166:167], v[118:119]
	v_cvt_pk_f32_fp8_e32 v[122:123], v121
	v_cvt_pk_f32_fp8_sdwa v[120:121], v121 src0_sel:WORD_1
	v_pk_fma_f32 v[118:119], v[122:123], v[168:169], v[118:119]
	s_nop 0
	v_pk_fma_f32 v[118:119], v[120:121], v[170:171], v[118:119]
	s_waitcnt vmcnt(28)
	v_cvt_pk_f32_fp8_sdwa v[120:121], v114 src0_sel:WORD_1
	v_add_f32_e32 v122, v118, v119
	v_cvt_pk_f32_fp8_e32 v[118:119], v114
	v_pk_fma_f32 v[118:119], v[118:119], v[154:155], 0 op_sel_hi:[1,1,0]
	s_nop 0
	v_pk_fma_f32 v[118:119], v[120:121], v[156:157], v[118:119]
	v_cvt_pk_f32_fp8_e32 v[120:121], v115
	v_cvt_pk_f32_fp8_sdwa v[114:115], v115 src0_sel:WORD_1
	v_pk_fma_f32 v[118:119], v[120:121], v[158:159], v[118:119]
	s_nop 0
	v_pk_fma_f32 v[114:115], v[114:115], v[162:163], v[118:119]
	v_cvt_pk_f32_fp8_e32 v[118:119], v116
	v_pk_fma_f32 v[114:115], v[118:119], v[164:165], v[114:115]
	v_cvt_pk_f32_fp8_sdwa v[118:119], v116 src0_sel:WORD_1
	v_pk_fma_f32 v[114:115], v[118:119], v[166:167], v[114:115]
	v_cvt_pk_f32_fp8_e32 v[118:119], v117
	v_cvt_pk_f32_fp8_sdwa v[116:117], v117 src0_sel:WORD_1
	v_pk_fma_f32 v[114:115], v[118:119], v[168:169], v[114:115]
	s_nop 0
	v_pk_fma_f32 v[114:115], v[116:117], v[170:171], v[114:115]
	s_waitcnt vmcnt(27)
	v_cvt_pk_f32_fp8_sdwa v[116:117], v110 src0_sel:WORD_1
	v_add_f32_e32 v118, v114, v115
	v_cvt_pk_f32_fp8_e32 v[114:115], v110
	v_pk_fma_f32 v[114:115], v[114:115], v[154:155], 0 op_sel_hi:[1,1,0]
	s_nop 0
	v_pk_fma_f32 v[114:115], v[116:117], v[156:157], v[114:115]
	v_cvt_pk_f32_fp8_e32 v[116:117], v111
	v_cvt_pk_f32_fp8_sdwa v[110:111], v111 src0_sel:WORD_1
	v_pk_fma_f32 v[114:115], v[116:117], v[158:159], v[114:115]
	s_nop 0
	v_pk_fma_f32 v[110:111], v[110:111], v[162:163], v[114:115]
	v_cvt_pk_f32_fp8_e32 v[114:115], v112
	v_pk_fma_f32 v[110:111], v[114:115], v[164:165], v[110:111]
	v_cvt_pk_f32_fp8_sdwa v[114:115], v112 src0_sel:WORD_1
	v_pk_fma_f32 v[110:111], v[114:115], v[166:167], v[110:111]
	v_cvt_pk_f32_fp8_e32 v[114:115], v113
	v_cvt_pk_f32_fp8_sdwa v[112:113], v113 src0_sel:WORD_1
	v_pk_fma_f32 v[110:111], v[114:115], v[168:169], v[110:111]
	s_nop 0
	v_pk_fma_f32 v[110:111], v[112:113], v[170:171], v[110:111]
	s_waitcnt vmcnt(25)
	v_cvt_pk_f32_fp8_sdwa v[112:113], v106 src0_sel:WORD_1
	v_add_f32_e32 v114, v110, v111
	v_cvt_pk_f32_fp8_e32 v[110:111], v106
	v_pk_fma_f32 v[110:111], v[110:111], v[154:155], 0 op_sel_hi:[1,1,0]
	s_nop 0
	v_pk_fma_f32 v[110:111], v[112:113], v[156:157], v[110:111]
	v_cvt_pk_f32_fp8_e32 v[112:113], v107
	v_cvt_pk_f32_fp8_sdwa v[106:107], v107 src0_sel:WORD_1
	v_pk_fma_f32 v[110:111], v[112:113], v[158:159], v[110:111]
	s_nop 0
	v_pk_fma_f32 v[106:107], v[106:107], v[162:163], v[110:111]
	v_cvt_pk_f32_fp8_e32 v[110:111], v108
	v_pk_fma_f32 v[106:107], v[110:111], v[164:165], v[106:107]
	v_cvt_pk_f32_fp8_sdwa v[110:111], v108 src0_sel:WORD_1
	v_pk_fma_f32 v[106:107], v[110:111], v[166:167], v[106:107]
	v_cvt_pk_f32_fp8_e32 v[110:111], v109
	v_cvt_pk_f32_fp8_sdwa v[108:109], v109 src0_sel:WORD_1
	v_pk_fma_f32 v[106:107], v[110:111], v[168:169], v[106:107]
	s_nop 0
	v_pk_fma_f32 v[106:107], v[108:109], v[170:171], v[106:107]
	s_waitcnt vmcnt(24)
	v_cvt_pk_f32_fp8_sdwa v[108:109], v102 src0_sel:WORD_1
	v_add_f32_e32 v110, v106, v107
	v_cvt_pk_f32_fp8_e32 v[106:107], v102
	v_pk_fma_f32 v[106:107], v[106:107], v[154:155], 0 op_sel_hi:[1,1,0]
	s_nop 0
	v_pk_fma_f32 v[106:107], v[108:109], v[156:157], v[106:107]
	v_cvt_pk_f32_fp8_e32 v[108:109], v103
	v_cvt_pk_f32_fp8_sdwa v[102:103], v103 src0_sel:WORD_1
	v_pk_fma_f32 v[106:107], v[108:109], v[158:159], v[106:107]
	s_nop 0
	v_pk_fma_f32 v[102:103], v[102:103], v[162:163], v[106:107]
	v_cvt_pk_f32_fp8_e32 v[106:107], v104
	v_pk_fma_f32 v[102:103], v[106:107], v[164:165], v[102:103]
	v_cvt_pk_f32_fp8_sdwa v[106:107], v104 src0_sel:WORD_1
	v_pk_fma_f32 v[102:103], v[106:107], v[166:167], v[102:103]
	v_cvt_pk_f32_fp8_e32 v[106:107], v105
	v_cvt_pk_f32_fp8_sdwa v[104:105], v105 src0_sel:WORD_1
	v_pk_fma_f32 v[102:103], v[106:107], v[168:169], v[102:103]
	s_nop 0
	v_pk_fma_f32 v[102:103], v[104:105], v[170:171], v[102:103]
	s_waitcnt vmcnt(23)
	v_cvt_pk_f32_fp8_sdwa v[104:105], v98 src0_sel:WORD_1
	v_add_f32_e32 v106, v102, v103
	v_cvt_pk_f32_fp8_e32 v[102:103], v98
	v_pk_fma_f32 v[102:103], v[102:103], v[154:155], 0 op_sel_hi:[1,1,0]
	s_nop 0
	v_pk_fma_f32 v[102:103], v[104:105], v[156:157], v[102:103]
	v_cvt_pk_f32_fp8_e32 v[104:105], v99
	v_cvt_pk_f32_fp8_sdwa v[98:99], v99 src0_sel:WORD_1
	v_pk_fma_f32 v[102:103], v[104:105], v[158:159], v[102:103]
	s_nop 0
	v_pk_fma_f32 v[98:99], v[98:99], v[162:163], v[102:103]
	v_cvt_pk_f32_fp8_e32 v[102:103], v100
	v_pk_fma_f32 v[98:99], v[102:103], v[164:165], v[98:99]
	v_cvt_pk_f32_fp8_sdwa v[102:103], v100 src0_sel:WORD_1
	v_pk_fma_f32 v[98:99], v[102:103], v[166:167], v[98:99]
	v_cvt_pk_f32_fp8_e32 v[102:103], v101
	v_cvt_pk_f32_fp8_sdwa v[100:101], v101 src0_sel:WORD_1
	v_pk_fma_f32 v[98:99], v[102:103], v[168:169], v[98:99]
	s_nop 0
	v_pk_fma_f32 v[98:99], v[100:101], v[170:171], v[98:99]
	s_waitcnt vmcnt(22)
	v_cvt_pk_f32_fp8_sdwa v[100:101], v94 src0_sel:WORD_1
	v_add_f32_e32 v102, v98, v99
	v_cvt_pk_f32_fp8_e32 v[98:99], v94
	v_pk_fma_f32 v[98:99], v[98:99], v[154:155], 0 op_sel_hi:[1,1,0]
	s_nop 0
	v_pk_fma_f32 v[98:99], v[100:101], v[156:157], v[98:99]
	v_cvt_pk_f32_fp8_e32 v[100:101], v95
	v_cvt_pk_f32_fp8_sdwa v[94:95], v95 src0_sel:WORD_1
	v_pk_fma_f32 v[98:99], v[100:101], v[158:159], v[98:99]
	s_nop 0
	v_pk_fma_f32 v[94:95], v[94:95], v[162:163], v[98:99]
	v_cvt_pk_f32_fp8_e32 v[98:99], v96
	v_pk_fma_f32 v[94:95], v[98:99], v[164:165], v[94:95]
	v_cvt_pk_f32_fp8_sdwa v[98:99], v96 src0_sel:WORD_1
	v_pk_fma_f32 v[94:95], v[98:99], v[166:167], v[94:95]
	v_cvt_pk_f32_fp8_e32 v[98:99], v97
	v_cvt_pk_f32_fp8_sdwa v[96:97], v97 src0_sel:WORD_1
	v_pk_fma_f32 v[94:95], v[98:99], v[168:169], v[94:95]
	s_nop 0
	v_pk_fma_f32 v[94:95], v[96:97], v[170:171], v[94:95]
	v_cvt_pk_f32_fp8_sdwa v[96:97], v90 src0_sel:WORD_1
	v_add_f32_e32 v98, v94, v95
	v_cvt_pk_f32_fp8_e32 v[94:95], v90
	v_pk_fma_f32 v[94:95], v[94:95], v[154:155], 0 op_sel_hi:[1,1,0]
	s_nop 0
	v_pk_fma_f32 v[94:95], v[96:97], v[156:157], v[94:95]
	v_cvt_pk_f32_fp8_e32 v[96:97], v91
	v_cvt_pk_f32_fp8_sdwa v[90:91], v91 src0_sel:WORD_1
	v_pk_fma_f32 v[94:95], v[96:97], v[158:159], v[94:95]
	s_nop 0
	v_pk_fma_f32 v[90:91], v[90:91], v[162:163], v[94:95]
	v_cvt_pk_f32_fp8_e32 v[94:95], v92
	v_pk_fma_f32 v[90:91], v[94:95], v[164:165], v[90:91]
	v_cvt_pk_f32_fp8_sdwa v[94:95], v92 src0_sel:WORD_1
	v_pk_fma_f32 v[90:91], v[94:95], v[166:167], v[90:91]
	v_cvt_pk_f32_fp8_e32 v[94:95], v93
	v_cvt_pk_f32_fp8_sdwa v[92:93], v93 src0_sel:WORD_1
	v_pk_fma_f32 v[90:91], v[94:95], v[168:169], v[90:91]
	s_nop 0
	v_pk_fma_f32 v[90:91], v[92:93], v[170:171], v[90:91]
	s_waitcnt vmcnt(21)
	v_cvt_pk_f32_fp8_sdwa v[92:93], v86 src0_sel:WORD_1
	v_add_f32_e32 v94, v90, v91
	v_cvt_pk_f32_fp8_e32 v[90:91], v86
	v_pk_fma_f32 v[90:91], v[90:91], v[154:155], 0 op_sel_hi:[1,1,0]
	s_nop 0
	v_pk_fma_f32 v[90:91], v[92:93], v[156:157], v[90:91]
	v_cvt_pk_f32_fp8_e32 v[92:93], v87
	v_cvt_pk_f32_fp8_sdwa v[86:87], v87 src0_sel:WORD_1
	v_pk_fma_f32 v[90:91], v[92:93], v[158:159], v[90:91]
	s_nop 0
	v_pk_fma_f32 v[86:87], v[86:87], v[162:163], v[90:91]
	v_cvt_pk_f32_fp8_e32 v[90:91], v88
	v_pk_fma_f32 v[86:87], v[90:91], v[164:165], v[86:87]
	v_cvt_pk_f32_fp8_sdwa v[90:91], v88 src0_sel:WORD_1
	v_pk_fma_f32 v[86:87], v[90:91], v[166:167], v[86:87]
	v_cvt_pk_f32_fp8_e32 v[90:91], v89
	v_cvt_pk_f32_fp8_sdwa v[88:89], v89 src0_sel:WORD_1
	v_pk_fma_f32 v[86:87], v[90:91], v[168:169], v[86:87]
	s_nop 0
	v_pk_fma_f32 v[86:87], v[88:89], v[170:171], v[86:87]
	s_waitcnt vmcnt(20)
	v_cvt_pk_f32_fp8_sdwa v[88:89], v82 src0_sel:WORD_1
	v_add_f32_e32 v90, v86, v87
	v_cvt_pk_f32_fp8_e32 v[86:87], v82
	v_pk_fma_f32 v[86:87], v[86:87], v[154:155], 0 op_sel_hi:[1,1,0]
	s_nop 0
	v_pk_fma_f32 v[86:87], v[88:89], v[156:157], v[86:87]
	v_cvt_pk_f32_fp8_e32 v[88:89], v83
	v_cvt_pk_f32_fp8_sdwa v[82:83], v83 src0_sel:WORD_1
	v_pk_fma_f32 v[86:87], v[88:89], v[158:159], v[86:87]
	s_nop 0
	v_pk_fma_f32 v[82:83], v[82:83], v[162:163], v[86:87]
	v_cvt_pk_f32_fp8_e32 v[86:87], v84
	v_pk_fma_f32 v[82:83], v[86:87], v[164:165], v[82:83]
	v_cvt_pk_f32_fp8_sdwa v[86:87], v84 src0_sel:WORD_1
	v_pk_fma_f32 v[82:83], v[86:87], v[166:167], v[82:83]
	v_cvt_pk_f32_fp8_e32 v[86:87], v85
	v_cvt_pk_f32_fp8_sdwa v[84:85], v85 src0_sel:WORD_1
	v_pk_fma_f32 v[82:83], v[86:87], v[168:169], v[82:83]
	s_nop 0
	v_pk_fma_f32 v[82:83], v[84:85], v[170:171], v[82:83]
	s_waitcnt vmcnt(19)
	v_cvt_pk_f32_fp8_sdwa v[84:85], v78 src0_sel:WORD_1
	v_add_f32_e32 v86, v82, v83
	v_cvt_pk_f32_fp8_e32 v[82:83], v78
	v_pk_fma_f32 v[82:83], v[82:83], v[154:155], 0 op_sel_hi:[1,1,0]
	s_nop 0
	v_pk_fma_f32 v[82:83], v[84:85], v[156:157], v[82:83]
	v_cvt_pk_f32_fp8_e32 v[84:85], v79
	v_cvt_pk_f32_fp8_sdwa v[78:79], v79 src0_sel:WORD_1
	v_pk_fma_f32 v[82:83], v[84:85], v[158:159], v[82:83]
	s_nop 0
	v_pk_fma_f32 v[78:79], v[78:79], v[162:163], v[82:83]
	v_cvt_pk_f32_fp8_e32 v[82:83], v80
	v_pk_fma_f32 v[78:79], v[82:83], v[164:165], v[78:79]
	v_cvt_pk_f32_fp8_sdwa v[82:83], v80 src0_sel:WORD_1
	v_pk_fma_f32 v[78:79], v[82:83], v[166:167], v[78:79]
	v_cvt_pk_f32_fp8_e32 v[82:83], v81
	v_cvt_pk_f32_fp8_sdwa v[80:81], v81 src0_sel:WORD_1
	v_pk_fma_f32 v[78:79], v[82:83], v[168:169], v[78:79]
	s_nop 0
	v_pk_fma_f32 v[78:79], v[80:81], v[170:171], v[78:79]
	s_waitcnt vmcnt(18)
	v_cvt_pk_f32_fp8_sdwa v[80:81], v74 src0_sel:WORD_1
	v_add_f32_e32 v82, v78, v79
	v_cvt_pk_f32_fp8_e32 v[78:79], v74
	v_pk_fma_f32 v[78:79], v[78:79], v[154:155], 0 op_sel_hi:[1,1,0]
	s_nop 0
	v_pk_fma_f32 v[78:79], v[80:81], v[156:157], v[78:79]
	v_cvt_pk_f32_fp8_e32 v[80:81], v75
	v_cvt_pk_f32_fp8_sdwa v[74:75], v75 src0_sel:WORD_1
	v_pk_fma_f32 v[78:79], v[80:81], v[158:159], v[78:79]
	s_nop 0
	v_pk_fma_f32 v[74:75], v[74:75], v[162:163], v[78:79]
	v_cvt_pk_f32_fp8_e32 v[78:79], v76
	v_pk_fma_f32 v[74:75], v[78:79], v[164:165], v[74:75]
	v_cvt_pk_f32_fp8_sdwa v[78:79], v76 src0_sel:WORD_1
	v_pk_fma_f32 v[74:75], v[78:79], v[166:167], v[74:75]
	v_cvt_pk_f32_fp8_e32 v[78:79], v77
	v_cvt_pk_f32_fp8_sdwa v[76:77], v77 src0_sel:WORD_1
	v_pk_fma_f32 v[74:75], v[78:79], v[168:169], v[74:75]
	s_nop 0
	v_pk_fma_f32 v[74:75], v[76:77], v[170:171], v[74:75]
	s_waitcnt vmcnt(17)
	v_cvt_pk_f32_fp8_sdwa v[76:77], v70 src0_sel:WORD_1
	v_add_f32_e32 v78, v74, v75
	v_cvt_pk_f32_fp8_e32 v[74:75], v70
	v_pk_fma_f32 v[74:75], v[74:75], v[154:155], 0 op_sel_hi:[1,1,0]
	s_nop 0
	v_pk_fma_f32 v[74:75], v[76:77], v[156:157], v[74:75]
	v_cvt_pk_f32_fp8_e32 v[76:77], v71
	v_cvt_pk_f32_fp8_sdwa v[70:71], v71 src0_sel:WORD_1
	v_pk_fma_f32 v[74:75], v[76:77], v[158:159], v[74:75]
	s_nop 0
	v_pk_fma_f32 v[70:71], v[70:71], v[162:163], v[74:75]
	v_cvt_pk_f32_fp8_e32 v[74:75], v72
	s_waitcnt vmcnt(15)
	v_cvt_pk_f32_fp8_e32 v[76:77], v65
	v_pk_fma_f32 v[70:71], v[74:75], v[164:165], v[70:71]
	v_cvt_pk_f32_fp8_sdwa v[74:75], v72 src0_sel:WORD_1
	v_pk_fma_f32 v[70:71], v[74:75], v[166:167], v[70:71]
	v_cvt_pk_f32_fp8_e32 v[74:75], v73
	v_cvt_pk_f32_fp8_sdwa v[72:73], v73 src0_sel:WORD_1
	v_pk_fma_f32 v[70:71], v[74:75], v[168:169], v[70:71]
	s_nop 0
	v_pk_fma_f32 v[70:71], v[72:73], v[170:171], v[70:71]
	v_cvt_pk_f32_fp8_sdwa v[72:73], v66 src0_sel:WORD_1
	v_add_f32_e32 v74, v70, v71
	v_cvt_pk_f32_fp8_e32 v[70:71], v66
	v_pk_fma_f32 v[70:71], v[70:71], v[154:155], 0 op_sel_hi:[1,1,0]
	s_nop 0
	v_pk_fma_f32 v[70:71], v[72:73], v[156:157], v[70:71]
	v_cvt_pk_f32_fp8_e32 v[72:73], v67
	v_cvt_pk_f32_fp8_sdwa v[66:67], v67 src0_sel:WORD_1
	v_pk_fma_f32 v[70:71], v[72:73], v[158:159], v[70:71]
	s_nop 0
	v_pk_fma_f32 v[66:67], v[66:67], v[162:163], v[70:71]
	v_cvt_pk_f32_fp8_e32 v[70:71], v68
	v_pk_fma_f32 v[66:67], v[70:71], v[164:165], v[66:67]
	v_cvt_pk_f32_fp8_sdwa v[70:71], v68 src0_sel:WORD_1
	v_pk_fma_f32 v[66:67], v[70:71], v[166:167], v[66:67]
	v_cvt_pk_f32_fp8_e32 v[70:71], v69
	v_cvt_pk_f32_fp8_sdwa v[68:69], v69 src0_sel:WORD_1
	v_pk_fma_f32 v[66:67], v[70:71], v[168:169], v[66:67]
	s_nop 0
	v_pk_fma_f32 v[66:67], v[68:69], v[170:171], v[66:67]
	v_add_f32_e32 v66, v66, v67
	v_cndmask_b32_e64 v127, v0, v98, s[6:7]
	v_cndmask_b32_e64 v0, v98, v0, s[6:7]
	v_cndmask_b32_e64 v128, v126, v94, s[6:7]
	v_cndmask_b32_e64 v126, v94, v126, s[6:7]
	v_cndmask_b32_e64 v129, v122, v90, s[6:7]
	v_cndmask_b32_e64 v122, v90, v122, s[6:7]
	v_cndmask_b32_e64 v123, v118, v86, s[6:7]
	v_cndmask_b32_e64 v118, v86, v118, s[6:7]
	v_cndmask_b32_e64 v124, v114, v82, s[6:7]
	v_cndmask_b32_e64 v114, v82, v114, s[6:7]
	v_cndmask_b32_e64 v125, v110, v78, s[6:7]
	v_cndmask_b32_e64 v110, v78, v110, s[6:7]
	v_cndmask_b32_e64 v119, v106, v74, s[6:7]
	v_cndmask_b32_e64 v106, v74, v106, s[6:7]
	v_cndmask_b32_e64 v120, v102, v66, s[6:7]
	v_cndmask_b32_e64 v102, v66, v102, s[6:7]
	v_add_f32_dpp v0, v127, v0 quad_perm:[1,0,3,2] row_mask:0xf bank_mask:0xf
	v_add_f32_dpp v126, v128, v126 quad_perm:[1,0,3,2] row_mask:0xf bank_mask:0xf
	v_add_f32_dpp v122, v129, v122 quad_perm:[1,0,3,2] row_mask:0xf bank_mask:0xf
	v_add_f32_dpp v118, v123, v118 quad_perm:[1,0,3,2] row_mask:0xf bank_mask:0xf
	v_add_f32_dpp v114, v124, v114 quad_perm:[1,0,3,2] row_mask:0xf bank_mask:0xf
	v_add_f32_dpp v110, v125, v110 quad_perm:[1,0,3,2] row_mask:0xf bank_mask:0xf
	v_add_f32_dpp v106, v119, v106 quad_perm:[1,0,3,2] row_mask:0xf bank_mask:0xf
	v_add_f32_dpp v102, v120, v102 quad_perm:[1,0,3,2] row_mask:0xf bank_mask:0xf
	v_cndmask_b32_e64 v127, v0, v114, s[8:9]
	v_cndmask_b32_e64 v0, v114, v0, s[8:9]
	v_cndmask_b32_e64 v128, v126, v110, s[8:9]
	v_cndmask_b32_e64 v126, v110, v126, s[8:9]
	v_cndmask_b32_e64 v129, v122, v106, s[8:9]
	v_cndmask_b32_e64 v122, v106, v122, s[8:9]
	v_cndmask_b32_e64 v123, v118, v102, s[8:9]
	v_cndmask_b32_e64 v118, v102, v118, s[8:9]
	v_add_f32_dpp v0, v127, v0 quad_perm:[2,3,0,1] row_mask:0xf bank_mask:0xf
	v_add_f32_dpp v126, v128, v126 quad_perm:[2,3,0,1] row_mask:0xf bank_mask:0xf
	v_add_f32_dpp v122, v129, v122 quad_perm:[2,3,0,1] row_mask:0xf bank_mask:0xf
	v_add_f32_dpp v118, v123, v118 quad_perm:[2,3,0,1] row_mask:0xf bank_mask:0xf
	v_cndmask_b32_e64 v127, v0, v122, s[10:11]
	v_cndmask_b32_e64 v0, v122, v0, s[10:11]
	v_cndmask_b32_e64 v128, v126, v118, s[10:11]
	v_cndmask_b32_e64 v126, v118, v126, s[10:11]
	v_mov_b32_dpp v129, v127 row_half_mirror row_mask:0xf bank_mask:0xf
	v_mov_b32_dpp v123, v128 row_half_mirror row_mask:0xf bank_mask:0xf
	s_nop 0
	v_add_f32_dpp v0, v129, v0 quad_perm:[3,2,1,0] row_mask:0xf bank_mask:0xf
	v_add_f32_dpp v126, v123, v126 quad_perm:[3,2,1,0] row_mask:0xf bank_mask:0xf
	v_cndmask_b32_e64 v127, v0, v126, s[12:13]
	v_cndmask_b32_e64 v0, v126, v0, s[12:13]
	s_nop 1
	v_add_f32_dpp v0, v127, v0 row_ror:8 row_mask:0xf bank_mask:0xf
	s_waitcnt vmcnt(14)
	v_cvt_pk_f32_fp8_e32 v[78:79], v58
	v_cvt_pk_f32_fp8_sdwa v[74:75], v64 src0_sel:WORD_1
	ds_bpermute_b32 v66, v214, v0
	s_waitcnt lgkmcnt(0)
	v_add_f32_e32 v0, v0, v66
	ds_bpermute_b32 v66, v215, v0
	s_waitcnt lgkmcnt(0)
	v_add_f32_e32 v0, v0, v66
	v_add_u32_e32 v66, s1, v151
	ds_read2st64_b32 v[66:67], v66 offset1:2
	s_waitcnt lgkmcnt(0)
	v_mul_f32_e32 v0, v66, v0
	v_mul_f32_e32 v66, 0x3d372713, v0
	v_mul_f32_e32 v66, v0, v66
	v_fma_f32 v66, v0, v66, v0
	v_mul_f32_e32 v66, 0xbfcc422a, v66
	v_mul_f32_e32 v66, 0x3fb8aa3b, v66
	v_exp_f32_e32 v66, v66
	s_nop 0
	v_add_f32_e32 v66, 1.0, v66
	v_div_scale_f32 v68, s[42:43], v66, v66, v0
	v_rcp_f32_e32 v69, v68
	s_nop 0
	v_fma_f32 v70, -v68, v69, 1.0
	v_fmac_f32_e32 v69, v70, v69
	v_div_scale_f32 v70, vcc, v0, v66, v0
	v_mul_f32_e32 v71, v70, v69
	v_fma_f32 v72, -v68, v71, v70
	v_fmac_f32_e32 v71, v72, v69
	v_fma_f32 v68, -v68, v71, v70
	v_div_fmas_f32 v68, v68, v69, v71
	v_div_fixup_f32 v0, v68, v66, v0
	v_mul_f32_e32 v0, v67, v0
	v_cvt_pk_f32_fp8_e32 v[66:67], v62
	v_cvt_pk_f32_fp8_sdwa v[68:69], v62 src0_sel:WORD_1
	v_cvt_pk_f32_fp8_e32 v[70:71], v63
	v_cvt_pk_f32_fp8_sdwa v[62:63], v63 src0_sel:WORD_1
	v_cvt_pk_f32_fp8_e32 v[72:73], v64
	v_cvt_pk_f32_fp8_sdwa v[64:65], v65 src0_sel:WORD_1
	v_readlane_b32 s0, v0, 0
	s_nop 1
	v_pk_fma_f32 v[66:67], v[66:67], s[0:1], v[184:185] op_sel_hi:[1,0,1]
	v_pk_fma_f32 v[68:69], v[68:69], s[0:1], v[186:187] op_sel_hi:[1,0,1]
	v_pk_fma_f32 v[70:71], v[70:71], s[0:1], v[182:183] op_sel_hi:[1,0,1]
	v_pk_fma_f32 v[62:63], v[62:63], s[0:1], v[180:181] op_sel_hi:[1,0,1]
	v_pk_fma_f32 v[72:73], v[72:73], s[0:1], v[178:179] op_sel_hi:[1,0,1]
	v_pk_fma_f32 v[74:75], v[74:75], s[0:1], v[176:177] op_sel_hi:[1,0,1]
	v_pk_fma_f32 v[76:77], v[76:77], s[0:1], v[174:175] op_sel_hi:[1,0,1]
	v_pk_fma_f32 v[64:65], v[64:65], s[0:1], v[172:173] op_sel_hi:[1,0,1]
	v_readlane_b32 s0, v0, 8
	s_nop 1
	v_pk_fma_f32 v[66:67], v[78:79], s[0:1], v[66:67] op_sel_hi:[1,0,1]
	v_cvt_pk_f32_fp8_sdwa v[78:79], v58 src0_sel:WORD_1
	v_pk_fma_f32 v[68:69], v[78:79], s[0:1], v[68:69] op_sel_hi:[1,0,1]
	v_cvt_pk_f32_fp8_e32 v[78:79], v59
	v_cvt_pk_f32_fp8_sdwa v[58:59], v59 src0_sel:WORD_1
	v_pk_fma_f32 v[70:71], v[78:79], s[0:1], v[70:71] op_sel_hi:[1,0,1]
	v_pk_fma_f32 v[58:59], v[58:59], s[0:1], v[62:63] op_sel_hi:[1,0,1]
	v_cvt_pk_f32_fp8_e32 v[62:63], v60
	v_pk_fma_f32 v[62:63], v[62:63], s[0:1], v[72:73] op_sel_hi:[1,0,1]
	v_cvt_pk_f32_fp8_sdwa v[72:73], v60 src0_sel:WORD_1
	v_pk_fma_f32 v[72:73], v[72:73], s[0:1], v[74:75] op_sel_hi:[1,0,1]
	v_cvt_pk_f32_fp8_e32 v[74:75], v61
	v_cvt_pk_f32_fp8_sdwa v[60:61], v61 src0_sel:WORD_1
	v_pk_fma_f32 v[74:75], v[74:75], s[0:1], v[76:77] op_sel_hi:[1,0,1]
	v_pk_fma_f32 v[60:61], v[60:61], s[0:1], v[64:65] op_sel_hi:[1,0,1]
	s_waitcnt vmcnt(13)
	v_cvt_pk_f32_fp8_e32 v[64:65], v54
	v_readlane_b32 s0, v0, 4
	s_nop 1
	v_pk_fma_f32 v[64:65], v[64:65], s[0:1], v[66:67] op_sel_hi:[1,0,1]
	v_cvt_pk_f32_fp8_sdwa v[66:67], v54 src0_sel:WORD_1
	v_pk_fma_f32 v[66:67], v[66:67], s[0:1], v[68:69] op_sel_hi:[1,0,1]
	v_cvt_pk_f32_fp8_e32 v[68:69], v55
	v_cvt_pk_f32_fp8_sdwa v[54:55], v55 src0_sel:WORD_1
	v_pk_fma_f32 v[68:69], v[68:69], s[0:1], v[70:71] op_sel_hi:[1,0,1]
	v_pk_fma_f32 v[54:55], v[54:55], s[0:1], v[58:59] op_sel_hi:[1,0,1]
	v_cvt_pk_f32_fp8_e32 v[58:59], v56
	v_cvt_pk_f32_fp8_e32 v[70:71], v57
	v_pk_fma_f32 v[58:59], v[58:59], s[0:1], v[62:63] op_sel_hi:[1,0,1]
	v_cvt_pk_f32_fp8_sdwa v[62:63], v56 src0_sel:WORD_1
	v_cvt_pk_f32_fp8_sdwa v[56:57], v57 src0_sel:WORD_1
	v_pk_fma_f32 v[70:71], v[70:71], s[0:1], v[74:75] op_sel_hi:[1,0,1]
	v_pk_fma_f32 v[62:63], v[62:63], s[0:1], v[72:73] op_sel_hi:[1,0,1]
	v_pk_fma_f32 v[56:57], v[56:57], s[0:1], v[60:61] op_sel_hi:[1,0,1]
	s_waitcnt vmcnt(12)
	v_cvt_pk_f32_fp8_e32 v[60:61], v50
	v_readlane_b32 s0, v0, 12
	s_nop 1
	v_pk_fma_f32 v[60:61], v[60:61], s[0:1], v[64:65] op_sel_hi:[1,0,1]
	v_cvt_pk_f32_fp8_sdwa v[64:65], v50 src0_sel:WORD_1
	v_pk_fma_f32 v[64:65], v[64:65], s[0:1], v[66:67] op_sel_hi:[1,0,1]
	v_cvt_pk_f32_fp8_e32 v[66:67], v51
	v_cvt_pk_f32_fp8_sdwa v[50:51], v51 src0_sel:WORD_1
	v_pk_fma_f32 v[66:67], v[66:67], s[0:1], v[68:69] op_sel_hi:[1,0,1]
	v_pk_fma_f32 v[50:51], v[50:51], s[0:1], v[54:55] op_sel_hi:[1,0,1]
	v_cvt_pk_f32_fp8_e32 v[54:55], v52
	v_pk_fma_f32 v[54:55], v[54:55], s[0:1], v[58:59] op_sel_hi:[1,0,1]
	v_cvt_pk_f32_fp8_sdwa v[58:59], v52 src0_sel:WORD_1
	v_pk_fma_f32 v[58:59], v[58:59], s[0:1], v[62:63] op_sel_hi:[1,0,1]
	v_cvt_pk_f32_fp8_e32 v[62:63], v53
	v_cvt_pk_f32_fp8_sdwa v[52:53], v53 src0_sel:WORD_1
	v_pk_fma_f32 v[62:63], v[62:63], s[0:1], v[70:71] op_sel_hi:[1,0,1]
	v_pk_fma_f32 v[52:53], v[52:53], s[0:1], v[56:57] op_sel_hi:[1,0,1]
	s_waitcnt vmcnt(11)
	v_cvt_pk_f32_fp8_e32 v[56:57], v46
	v_readlane_b32 s0, v0, 2
	s_nop 1
	v_pk_fma_f32 v[56:57], v[56:57], s[0:1], v[60:61] op_sel_hi:[1,0,1]
	v_cvt_pk_f32_fp8_sdwa v[60:61], v46 src0_sel:WORD_1
	v_pk_fma_f32 v[60:61], v[60:61], s[0:1], v[64:65] op_sel_hi:[1,0,1]
	v_cvt_pk_f32_fp8_e32 v[64:65], v47
	v_cvt_pk_f32_fp8_sdwa v[46:47], v47 src0_sel:WORD_1
	v_pk_fma_f32 v[64:65], v[64:65], s[0:1], v[66:67] op_sel_hi:[1,0,1]
	v_pk_fma_f32 v[46:47], v[46:47], s[0:1], v[50:51] op_sel_hi:[1,0,1]
	v_cvt_pk_f32_fp8_e32 v[50:51], v48
	v_pk_fma_f32 v[50:51], v[50:51], s[0:1], v[54:55] op_sel_hi:[1,0,1]
	v_cvt_pk_f32_fp8_sdwa v[54:55], v48 src0_sel:WORD_1
	v_pk_fma_f32 v[54:55], v[54:55], s[0:1], v[58:59] op_sel_hi:[1,0,1]
	v_cvt_pk_f32_fp8_e32 v[58:59], v49
	v_cvt_pk_f32_fp8_sdwa v[48:49], v49 src0_sel:WORD_1
	v_pk_fma_f32 v[58:59], v[58:59], s[0:1], v[62:63] op_sel_hi:[1,0,1]
	v_pk_fma_f32 v[48:49], v[48:49], s[0:1], v[52:53] op_sel_hi:[1,0,1]
	s_waitcnt vmcnt(10)
	v_cvt_pk_f32_fp8_e32 v[52:53], v42
	v_readlane_b32 s0, v0, 10
	s_nop 1
	v_pk_fma_f32 v[52:53], v[52:53], s[0:1], v[56:57] op_sel_hi:[1,0,1]
	v_cvt_pk_f32_fp8_sdwa v[56:57], v42 src0_sel:WORD_1
	v_pk_fma_f32 v[56:57], v[56:57], s[0:1], v[60:61] op_sel_hi:[1,0,1]
	v_cvt_pk_f32_fp8_e32 v[60:61], v43
	v_cvt_pk_f32_fp8_sdwa v[42:43], v43 src0_sel:WORD_1
	v_pk_fma_f32 v[60:61], v[60:61], s[0:1], v[64:65] op_sel_hi:[1,0,1]
	v_pk_fma_f32 v[42:43], v[42:43], s[0:1], v[46:47] op_sel_hi:[1,0,1]
	v_cvt_pk_f32_fp8_e32 v[46:47], v44
	v_pk_fma_f32 v[46:47], v[46:47], s[0:1], v[50:51] op_sel_hi:[1,0,1]
	v_cvt_pk_f32_fp8_sdwa v[50:51], v44 src0_sel:WORD_1
	v_pk_fma_f32 v[50:51], v[50:51], s[0:1], v[54:55] op_sel_hi:[1,0,1]
	v_cvt_pk_f32_fp8_e32 v[54:55], v45
	v_cvt_pk_f32_fp8_sdwa v[44:45], v45 src0_sel:WORD_1
	v_pk_fma_f32 v[54:55], v[54:55], s[0:1], v[58:59] op_sel_hi:[1,0,1]
	v_pk_fma_f32 v[44:45], v[44:45], s[0:1], v[48:49] op_sel_hi:[1,0,1]
	s_waitcnt vmcnt(9)
	v_cvt_pk_f32_fp8_e32 v[48:49], v38
	v_readlane_b32 s0, v0, 6
	s_nop 1
	v_pk_fma_f32 v[48:49], v[48:49], s[0:1], v[52:53] op_sel_hi:[1,0,1]
	v_cvt_pk_f32_fp8_sdwa v[52:53], v38 src0_sel:WORD_1
	v_pk_fma_f32 v[52:53], v[52:53], s[0:1], v[56:57] op_sel_hi:[1,0,1]
	v_cvt_pk_f32_fp8_e32 v[56:57], v39
	v_cvt_pk_f32_fp8_sdwa v[38:39], v39 src0_sel:WORD_1
	v_pk_fma_f32 v[56:57], v[56:57], s[0:1], v[60:61] op_sel_hi:[1,0,1]
	v_pk_fma_f32 v[38:39], v[38:39], s[0:1], v[42:43] op_sel_hi:[1,0,1]
	v_cvt_pk_f32_fp8_e32 v[42:43], v40
	v_pk_fma_f32 v[42:43], v[42:43], s[0:1], v[46:47] op_sel_hi:[1,0,1]
	v_cvt_pk_f32_fp8_sdwa v[46:47], v40 src0_sel:WORD_1
	v_pk_fma_f32 v[46:47], v[46:47], s[0:1], v[50:51] op_sel_hi:[1,0,1]
	v_cvt_pk_f32_fp8_e32 v[50:51], v41
	v_cvt_pk_f32_fp8_sdwa v[40:41], v41 src0_sel:WORD_1
	v_pk_fma_f32 v[50:51], v[50:51], s[0:1], v[54:55] op_sel_hi:[1,0,1]
	v_pk_fma_f32 v[40:41], v[40:41], s[0:1], v[44:45] op_sel_hi:[1,0,1]
	s_waitcnt vmcnt(8)
	v_cvt_pk_f32_fp8_e32 v[44:45], v34
	v_readlane_b32 s0, v0, 14
	s_nop 1
	v_pk_fma_f32 v[44:45], v[44:45], s[0:1], v[48:49] op_sel_hi:[1,0,1]
	v_cvt_pk_f32_fp8_sdwa v[48:49], v34 src0_sel:WORD_1
	v_pk_fma_f32 v[48:49], v[48:49], s[0:1], v[52:53] op_sel_hi:[1,0,1]
	v_cvt_pk_f32_fp8_e32 v[52:53], v35
	v_cvt_pk_f32_fp8_sdwa v[34:35], v35 src0_sel:WORD_1
	v_pk_fma_f32 v[52:53], v[52:53], s[0:1], v[56:57] op_sel_hi:[1,0,1]
	v_pk_fma_f32 v[34:35], v[34:35], s[0:1], v[38:39] op_sel_hi:[1,0,1]
	v_cvt_pk_f32_fp8_e32 v[38:39], v36
	v_pk_fma_f32 v[38:39], v[38:39], s[0:1], v[42:43] op_sel_hi:[1,0,1]
	v_cvt_pk_f32_fp8_sdwa v[42:43], v36 src0_sel:WORD_1
	v_pk_fma_f32 v[42:43], v[42:43], s[0:1], v[46:47] op_sel_hi:[1,0,1]
	v_cvt_pk_f32_fp8_e32 v[46:47], v37
	v_cvt_pk_f32_fp8_sdwa v[36:37], v37 src0_sel:WORD_1
	v_pk_fma_f32 v[46:47], v[46:47], s[0:1], v[50:51] op_sel_hi:[1,0,1]
	v_pk_fma_f32 v[36:37], v[36:37], s[0:1], v[40:41] op_sel_hi:[1,0,1]
	s_waitcnt vmcnt(7)
	v_cvt_pk_f32_fp8_e32 v[40:41], v30
	v_readlane_b32 s0, v0, 1
	s_nop 1
	v_pk_fma_f32 v[40:41], v[40:41], s[0:1], v[44:45] op_sel_hi:[1,0,1]
	v_cvt_pk_f32_fp8_sdwa v[44:45], v30 src0_sel:WORD_1
	v_pk_fma_f32 v[44:45], v[44:45], s[0:1], v[48:49] op_sel_hi:[1,0,1]
	v_cvt_pk_f32_fp8_e32 v[48:49], v31
	v_cvt_pk_f32_fp8_sdwa v[30:31], v31 src0_sel:WORD_1
	v_pk_fma_f32 v[48:49], v[48:49], s[0:1], v[52:53] op_sel_hi:[1,0,1]
	v_pk_fma_f32 v[30:31], v[30:31], s[0:1], v[34:35] op_sel_hi:[1,0,1]
	v_cvt_pk_f32_fp8_e32 v[34:35], v32
	v_pk_fma_f32 v[34:35], v[34:35], s[0:1], v[38:39] op_sel_hi:[1,0,1]
	v_cvt_pk_f32_fp8_sdwa v[38:39], v32 src0_sel:WORD_1
	v_pk_fma_f32 v[38:39], v[38:39], s[0:1], v[42:43] op_sel_hi:[1,0,1]
	v_cvt_pk_f32_fp8_e32 v[42:43], v33
	v_cvt_pk_f32_fp8_sdwa v[32:33], v33 src0_sel:WORD_1
	v_pk_fma_f32 v[42:43], v[42:43], s[0:1], v[46:47] op_sel_hi:[1,0,1]
	v_pk_fma_f32 v[32:33], v[32:33], s[0:1], v[36:37] op_sel_hi:[1,0,1]
	s_waitcnt vmcnt(6)
	v_cvt_pk_f32_fp8_e32 v[36:37], v26
	v_readlane_b32 s0, v0, 9
	s_nop 1
	v_pk_fma_f32 v[36:37], v[36:37], s[0:1], v[40:41] op_sel_hi:[1,0,1]
	v_cvt_pk_f32_fp8_sdwa v[40:41], v26 src0_sel:WORD_1
	v_pk_fma_f32 v[40:41], v[40:41], s[0:1], v[44:45] op_sel_hi:[1,0,1]
	v_cvt_pk_f32_fp8_e32 v[44:45], v27
	v_cvt_pk_f32_fp8_sdwa v[26:27], v27 src0_sel:WORD_1
	v_pk_fma_f32 v[44:45], v[44:45], s[0:1], v[48:49] op_sel_hi:[1,0,1]
	v_pk_fma_f32 v[26:27], v[26:27], s[0:1], v[30:31] op_sel_hi:[1,0,1]
	v_cvt_pk_f32_fp8_e32 v[30:31], v28
	v_pk_fma_f32 v[30:31], v[30:31], s[0:1], v[34:35] op_sel_hi:[1,0,1]
	v_cvt_pk_f32_fp8_sdwa v[34:35], v28 src0_sel:WORD_1
	v_pk_fma_f32 v[34:35], v[34:35], s[0:1], v[38:39] op_sel_hi:[1,0,1]
	v_cvt_pk_f32_fp8_e32 v[38:39], v29
	v_cvt_pk_f32_fp8_sdwa v[28:29], v29 src0_sel:WORD_1
	v_pk_fma_f32 v[38:39], v[38:39], s[0:1], v[42:43] op_sel_hi:[1,0,1]
	v_pk_fma_f32 v[28:29], v[28:29], s[0:1], v[32:33] op_sel_hi:[1,0,1]
	s_waitcnt vmcnt(5)
	v_cvt_pk_f32_fp8_e32 v[32:33], v22
	v_readlane_b32 s0, v0, 5
	s_nop 1
	v_pk_fma_f32 v[32:33], v[32:33], s[0:1], v[36:37] op_sel_hi:[1,0,1]
	v_cvt_pk_f32_fp8_sdwa v[36:37], v22 src0_sel:WORD_1
	v_pk_fma_f32 v[36:37], v[36:37], s[0:1], v[40:41] op_sel_hi:[1,0,1]
	v_cvt_pk_f32_fp8_e32 v[40:41], v23
	v_cvt_pk_f32_fp8_sdwa v[22:23], v23 src0_sel:WORD_1
	v_pk_fma_f32 v[40:41], v[40:41], s[0:1], v[44:45] op_sel_hi:[1,0,1]
	v_pk_fma_f32 v[22:23], v[22:23], s[0:1], v[26:27] op_sel_hi:[1,0,1]
	v_cvt_pk_f32_fp8_e32 v[26:27], v24
	v_pk_fma_f32 v[26:27], v[26:27], s[0:1], v[30:31] op_sel_hi:[1,0,1]
	v_cvt_pk_f32_fp8_sdwa v[30:31], v24 src0_sel:WORD_1
	v_pk_fma_f32 v[30:31], v[30:31], s[0:1], v[34:35] op_sel_hi:[1,0,1]
	v_cvt_pk_f32_fp8_e32 v[34:35], v25
	v_cvt_pk_f32_fp8_sdwa v[24:25], v25 src0_sel:WORD_1
	v_pk_fma_f32 v[34:35], v[34:35], s[0:1], v[38:39] op_sel_hi:[1,0,1]
	v_pk_fma_f32 v[24:25], v[24:25], s[0:1], v[28:29] op_sel_hi:[1,0,1]
	s_waitcnt vmcnt(4)
	v_cvt_pk_f32_fp8_e32 v[28:29], v18
	v_readlane_b32 s0, v0, 13
	s_nop 1
	v_pk_fma_f32 v[28:29], v[28:29], s[0:1], v[32:33] op_sel_hi:[1,0,1]
	v_cvt_pk_f32_fp8_sdwa v[32:33], v18 src0_sel:WORD_1
	v_pk_fma_f32 v[32:33], v[32:33], s[0:1], v[36:37] op_sel_hi:[1,0,1]
	v_cvt_pk_f32_fp8_e32 v[36:37], v19
	v_cvt_pk_f32_fp8_sdwa v[18:19], v19 src0_sel:WORD_1
	v_pk_fma_f32 v[36:37], v[36:37], s[0:1], v[40:41] op_sel_hi:[1,0,1]
	v_pk_fma_f32 v[18:19], v[18:19], s[0:1], v[22:23] op_sel_hi:[1,0,1]
	v_cvt_pk_f32_fp8_e32 v[22:23], v20
	v_pk_fma_f32 v[22:23], v[22:23], s[0:1], v[26:27] op_sel_hi:[1,0,1]
	v_cvt_pk_f32_fp8_sdwa v[26:27], v20 src0_sel:WORD_1
	v_pk_fma_f32 v[26:27], v[26:27], s[0:1], v[30:31] op_sel_hi:[1,0,1]
	v_cvt_pk_f32_fp8_e32 v[30:31], v21
	v_cvt_pk_f32_fp8_sdwa v[20:21], v21 src0_sel:WORD_1
	v_pk_fma_f32 v[30:31], v[30:31], s[0:1], v[34:35] op_sel_hi:[1,0,1]
	v_pk_fma_f32 v[20:21], v[20:21], s[0:1], v[24:25] op_sel_hi:[1,0,1]
	s_waitcnt vmcnt(3)
	v_cvt_pk_f32_fp8_e32 v[24:25], v14
	v_readlane_b32 s0, v0, 3
	s_nop 1
	v_pk_fma_f32 v[24:25], v[24:25], s[0:1], v[28:29] op_sel_hi:[1,0,1]
	v_cvt_pk_f32_fp8_sdwa v[28:29], v14 src0_sel:WORD_1
	v_pk_fma_f32 v[28:29], v[28:29], s[0:1], v[32:33] op_sel_hi:[1,0,1]
	v_cvt_pk_f32_fp8_e32 v[32:33], v15
	v_cvt_pk_f32_fp8_sdwa v[14:15], v15 src0_sel:WORD_1
	v_pk_fma_f32 v[32:33], v[32:33], s[0:1], v[36:37] op_sel_hi:[1,0,1]
	v_pk_fma_f32 v[14:15], v[14:15], s[0:1], v[18:19] op_sel_hi:[1,0,1]
	v_cvt_pk_f32_fp8_e32 v[18:19], v16
	v_pk_fma_f32 v[18:19], v[18:19], s[0:1], v[22:23] op_sel_hi:[1,0,1]
	v_cvt_pk_f32_fp8_sdwa v[22:23], v16 src0_sel:WORD_1
	v_pk_fma_f32 v[22:23], v[22:23], s[0:1], v[26:27] op_sel_hi:[1,0,1]
	v_cvt_pk_f32_fp8_e32 v[26:27], v17
	v_cvt_pk_f32_fp8_sdwa v[16:17], v17 src0_sel:WORD_1
	v_pk_fma_f32 v[26:27], v[26:27], s[0:1], v[30:31] op_sel_hi:[1,0,1]
	v_pk_fma_f32 v[16:17], v[16:17], s[0:1], v[20:21] op_sel_hi:[1,0,1]
	s_waitcnt vmcnt(2)
	v_cvt_pk_f32_fp8_e32 v[20:21], v10
	v_readlane_b32 s0, v0, 11
	s_nop 1
	v_pk_fma_f32 v[20:21], v[20:21], s[0:1], v[24:25] op_sel_hi:[1,0,1]
	v_cvt_pk_f32_fp8_sdwa v[24:25], v10 src0_sel:WORD_1
	v_pk_fma_f32 v[24:25], v[24:25], s[0:1], v[28:29] op_sel_hi:[1,0,1]
	v_cvt_pk_f32_fp8_e32 v[28:29], v11
	v_cvt_pk_f32_fp8_sdwa v[10:11], v11 src0_sel:WORD_1
	v_pk_fma_f32 v[28:29], v[28:29], s[0:1], v[32:33] op_sel_hi:[1,0,1]
	v_pk_fma_f32 v[10:11], v[10:11], s[0:1], v[14:15] op_sel_hi:[1,0,1]
	v_cvt_pk_f32_fp8_e32 v[14:15], v12
	v_pk_fma_f32 v[14:15], v[14:15], s[0:1], v[18:19] op_sel_hi:[1,0,1]
	v_cvt_pk_f32_fp8_sdwa v[18:19], v12 src0_sel:WORD_1
	v_pk_fma_f32 v[18:19], v[18:19], s[0:1], v[22:23] op_sel_hi:[1,0,1]
	v_cvt_pk_f32_fp8_e32 v[22:23], v13
	v_cvt_pk_f32_fp8_sdwa v[12:13], v13 src0_sel:WORD_1
	v_pk_fma_f32 v[22:23], v[22:23], s[0:1], v[26:27] op_sel_hi:[1,0,1]
	v_pk_fma_f32 v[12:13], v[12:13], s[0:1], v[16:17] op_sel_hi:[1,0,1]
	s_waitcnt vmcnt(1)
	v_cvt_pk_f32_fp8_e32 v[16:17], v6
	v_readlane_b32 s0, v0, 7
	s_nop 1
	v_pk_fma_f32 v[16:17], v[16:17], s[0:1], v[20:21] op_sel_hi:[1,0,1]
	v_cvt_pk_f32_fp8_sdwa v[20:21], v6 src0_sel:WORD_1
	v_pk_fma_f32 v[20:21], v[20:21], s[0:1], v[24:25] op_sel_hi:[1,0,1]
	v_cvt_pk_f32_fp8_e32 v[24:25], v7
	v_cvt_pk_f32_fp8_sdwa v[6:7], v7 src0_sel:WORD_1
	v_pk_fma_f32 v[24:25], v[24:25], s[0:1], v[28:29] op_sel_hi:[1,0,1]
	v_pk_fma_f32 v[6:7], v[6:7], s[0:1], v[10:11] op_sel_hi:[1,0,1]
	v_cvt_pk_f32_fp8_e32 v[10:11], v8
	v_pk_fma_f32 v[10:11], v[10:11], s[0:1], v[14:15] op_sel_hi:[1,0,1]
	v_cvt_pk_f32_fp8_sdwa v[14:15], v8 src0_sel:WORD_1
	v_pk_fma_f32 v[14:15], v[14:15], s[0:1], v[18:19] op_sel_hi:[1,0,1]
	v_cvt_pk_f32_fp8_e32 v[18:19], v9
	v_cvt_pk_f32_fp8_sdwa v[8:9], v9 src0_sel:WORD_1
	v_pk_fma_f32 v[18:19], v[18:19], s[0:1], v[22:23] op_sel_hi:[1,0,1]
	v_pk_fma_f32 v[8:9], v[8:9], s[0:1], v[12:13] op_sel_hi:[1,0,1]
	s_waitcnt vmcnt(0)
	v_cvt_pk_f32_fp8_e32 v[12:13], v2
	v_readlane_b32 s0, v0, 15
	s_nop 1
	v_pk_fma_f32 v[184:185], v[12:13], s[0:1], v[16:17] op_sel_hi:[1,0,1]
	v_cvt_pk_f32_fp8_sdwa v[12:13], v2 src0_sel:WORD_1
	v_pk_fma_f32 v[186:187], v[12:13], s[0:1], v[20:21] op_sel_hi:[1,0,1]
	v_cvt_pk_f32_fp8_e32 v[12:13], v3
	v_cvt_pk_f32_fp8_sdwa v[2:3], v3 src0_sel:WORD_1
	v_pk_fma_f32 v[182:183], v[12:13], s[0:1], v[24:25] op_sel_hi:[1,0,1]
	v_pk_fma_f32 v[180:181], v[2:3], s[0:1], v[6:7] op_sel_hi:[1,0,1]
	v_cvt_pk_f32_fp8_e32 v[2:3], v4
	v_pk_fma_f32 v[178:179], v[2:3], s[0:1], v[10:11] op_sel_hi:[1,0,1]
	v_cvt_pk_f32_fp8_sdwa v[2:3], v4 src0_sel:WORD_1
	v_pk_fma_f32 v[176:177], v[2:3], s[0:1], v[14:15] op_sel_hi:[1,0,1]
	v_cvt_pk_f32_fp8_e32 v[2:3], v5
	v_pk_fma_f32 v[174:175], v[2:3], s[0:1], v[18:19] op_sel_hi:[1,0,1]
	v_cvt_pk_f32_fp8_sdwa v[2:3], v5 src0_sel:WORD_1
	v_pk_fma_f32 v[172:173], v[2:3], s[0:1], v[8:9] op_sel_hi:[1,0,1]
	s_add_i32 s1, s1, 64
	s_cmpk_lg_i32 s1, 0x200
	s_cbranch_scc1 .LBB0_870
	v_add_u32_e32 v0, 0xfffff000, v152
	v_lshrrev_b32_e32 v0, 10, v0
	v_add_u32_e32 v0, 1, v0
	v_cmp_lt_i32_e32 vcc, s57, v152
	v_mov_b64_e32 v[2:3], s[16:17]
	v_lshlrev_b64 v[4:5], 12, v[152:153]
	v_cndmask_b32_e32 v0, 0, v0, vcc
	v_add_u32_e32 v46, s40, v0
	v_mad_u64_u32 v[2:3], s[0:1], v46, s63, v[2:3]
	v_lshlrev_b32_e32 v0, 2, v136
	v_lshl_add_u64 v[2:3], v[2:3], 0, v[0:1]
	s_mov_b64 s[0:1], 0x5000
	v_lshl_add_u64 v[52:53], v[2:3], 0, s[0:1]
	s_movk_i32 s0, 0x5000
	v_lshl_add_u64 v[40:41], v[142:143], 0, v[4:5]
	v_add_co_u32_e32 v2, vcc, s0, v2
	global_load_dwordx4 v[10:13], v[40:41], off
	s_nop 0
	v_addc_co_u32_e32 v3, vcc, 0, v3, vcc
	global_load_dwordx4 v[16:19], v[2:3], off
	s_nop 0
	global_load_dwordx4 v[2:5], v[146:147], off
	global_load_dwordx4 v[6:9], v[148:149], off
	v_lshlrev_b64 v[38:39], 10, v[152:153]
	s_mov_b64 s[0:1], -1
	s_waitcnt vmcnt(2)
	v_pk_mul_f32 v[14:15], v[184:185], v[16:17]
	s_nop 0
	v_pk_fma_f32 v[16:17], v[10:11], s[86:87], v[14:15] op_sel_hi:[1,0,1]
	s_nop 0
	v_add_f32_e32 v10, 0, v16
	v_add_f32_e32 v20, v17, v10
	v_pk_mul_f32 v[10:11], v[186:187], v[18:19]
	s_nop 0
	v_pk_fma_f32 v[14:15], v[12:13], s[86:87], v[10:11] op_sel_hi:[1,0,1]
	s_nop 0
	v_add_f32_e32 v10, v14, v20
	v_add_f32_e32 v30, v15, v10
	global_load_dwordx4 v[22:25], v[40:41], off offset:1024
	global_load_dwordx4 v[26:29], v[52:53], off offset:1024
	global_load_dwordx4 v[10:13], v[146:147], off offset:1024
	global_load_dwordx4 v[18:21], v[148:149], off offset:1024
	s_waitcnt vmcnt(2)
	v_pk_mul_f32 v[26:27], v[182:183], v[26:27]
	s_nop 0
	v_pk_fma_f32 v[44:45], v[22:23], s[86:87], v[26:27] op_sel_hi:[1,0,1]
	s_nop 0
	v_add_f32_e32 v22, v44, v30
	v_add_f32_e32 v26, v45, v22
	v_pk_mul_f32 v[22:23], v[180:181], v[28:29]
	s_nop 0
	v_pk_fma_f32 v[42:43], v[24:25], s[86:87], v[22:23] op_sel_hi:[1,0,1]
	s_nop 0
	v_add_f32_e32 v22, v42, v26
	v_add_f32_e32 v47, v43, v22
	global_load_dwordx4 v[30:33], v[40:41], off offset:2048
	global_load_dwordx4 v[34:37], v[52:53], off offset:2048
	global_load_dwordx4 v[22:25], v[146:147], off offset:2048
	global_load_dwordx4 v[26:29], v[148:149], off offset:2048
	s_waitcnt vmcnt(2)
	v_pk_mul_f32 v[34:35], v[178:179], v[34:35]
	s_nop 0
	v_pk_fma_f32 v[56:57], v[30:31], s[86:87], v[34:35] op_sel_hi:[1,0,1]
	s_nop 0
	v_add_f32_e32 v30, v56, v47
	v_add_f32_e32 v34, v57, v30
	v_pk_mul_f32 v[30:31], v[176:177], v[36:37]
	s_nop 0
	v_pk_fma_f32 v[58:59], v[32:33], s[86:87], v[30:31] op_sel_hi:[1,0,1]
	s_nop 0
	v_add_f32_e32 v30, v58, v34
	v_add_f32_e32 v47, v59, v30
	global_load_dwordx4 v[48:51], v[40:41], off offset:3072
	s_nop 0
	global_load_dwordx4 v[52:55], v[52:53], off offset:3072
	s_nop 0
	global_load_dwordx4 v[30:33], v[146:147], off offset:3072
	global_load_dwordx4 v[34:37], v[148:149], off offset:3072
	s_waitcnt vmcnt(2)
	v_pk_mul_f32 v[52:53], v[174:175], v[52:53]
	s_nop 0
	v_pk_fma_f32 v[48:49], v[48:49], s[86:87], v[52:53] op_sel_hi:[1,0,1]
	v_pk_mul_f32 v[52:53], v[172:173], v[54:55]
	v_add_f32_e32 v47, v48, v47
	v_add_f32_e32 v47, v49, v47
	v_pk_fma_f32 v[50:51], v[50:51], s[86:87], v[52:53] op_sel_hi:[1,0,1]
	s_nop 0
	v_add_f32_e32 v47, v50, v47
	v_add_f32_e32 v47, v51, v47
	ds_bpermute_b32 v52, v215, v47
	s_waitcnt lgkmcnt(0)
	v_add_f32_e32 v47, v47, v52
	ds_bpermute_b32 v52, v214, v47
	s_waitcnt lgkmcnt(0)
	v_add_f32_e32 v47, v47, v52
	ds_bpermute_b32 v52, v216, v47
	s_waitcnt lgkmcnt(0)
	v_add_f32_e32 v47, v47, v52
	ds_bpermute_b32 v52, v217, v47
	s_waitcnt lgkmcnt(0)
	v_add_f32_e32 v47, v47, v52
	ds_bpermute_b32 v52, v218, v47
	s_waitcnt lgkmcnt(0)
	v_add_f32_e32 v47, v47, v52
	ds_bpermute_b32 v52, v219, v47
	s_waitcnt lgkmcnt(0)
	v_add_f32_e32 v47, v47, v52
	v_mul_f32_e32 v52, 0x3a800000, v47
	v_pk_add_f32 v[16:17], v[16:17], v[52:53] op_sel_hi:[1,0] neg_lo:[0,1] neg_hi:[0,1]
	v_pk_add_f32 v[60:61], v[14:15], v[52:53] op_sel_hi:[1,0] neg_lo:[0,1] neg_hi:[0,1]
	v_pk_mul_f32 v[54:55], v[16:17], v[16:17]
	v_pk_mul_f32 v[14:15], v[60:61], v[60:61]
	v_add_f32_e32 v47, v54, v55
	v_pk_add_f32 v[44:45], v[44:45], v[52:53] op_sel_hi:[1,0] neg_lo:[0,1] neg_hi:[0,1]
	v_add_f32_e32 v14, v14, v47
	v_pk_mul_f32 v[62:63], v[44:45], v[44:45]
	v_add_f32_e32 v14, v15, v14
	v_pk_add_f32 v[42:43], v[42:43], v[52:53] op_sel_hi:[1,0] neg_lo:[0,1] neg_hi:[0,1]
	v_add_f32_e32 v14, v62, v14
	v_pk_mul_f32 v[64:65], v[42:43], v[42:43]
	v_add_f32_e32 v14, v63, v14
	v_pk_add_f32 v[56:57], v[56:57], v[52:53] op_sel_hi:[1,0] neg_lo:[0,1] neg_hi:[0,1]
	v_add_f32_e32 v14, v64, v14
	v_pk_mul_f32 v[66:67], v[56:57], v[56:57]
	v_add_f32_e32 v14, v65, v14
	v_pk_add_f32 v[58:59], v[58:59], v[52:53] op_sel_hi:[1,0] neg_lo:[0,1] neg_hi:[0,1]
	v_add_f32_e32 v14, v66, v14
	v_pk_mul_f32 v[68:69], v[58:59], v[58:59]
	v_add_f32_e32 v14, v67, v14
	v_pk_add_f32 v[48:49], v[48:49], v[52:53] op_sel_hi:[1,0] neg_lo:[0,1] neg_hi:[0,1]
	v_add_f32_e32 v14, v68, v14
	v_pk_mul_f32 v[70:71], v[48:49], v[48:49]
	v_add_f32_e32 v14, v69, v14
	v_pk_add_f32 v[50:51], v[50:51], v[52:53] op_sel_hi:[1,0] neg_lo:[0,1] neg_hi:[0,1]
	v_add_f32_e32 v14, v70, v14
	v_pk_mul_f32 v[52:53], v[50:51], v[50:51]
	v_add_f32_e32 v14, v71, v14
	v_add_f32_e32 v14, v52, v14
	v_add_f32_e32 v14, v53, v14
	ds_bpermute_b32 v15, v215, v14
	s_waitcnt lgkmcnt(0)
	v_add_f32_e32 v14, v14, v15
	ds_bpermute_b32 v15, v214, v14
	s_waitcnt lgkmcnt(0)
	v_add_f32_e32 v14, v14, v15
	ds_bpermute_b32 v15, v216, v14
	s_waitcnt lgkmcnt(0)
	v_add_f32_e32 v14, v14, v15
	ds_bpermute_b32 v15, v217, v14
	s_waitcnt lgkmcnt(0)
	v_add_f32_e32 v14, v14, v15
	ds_bpermute_b32 v15, v218, v14
	s_waitcnt lgkmcnt(0)
	v_add_f32_e32 v14, v14, v15
	ds_bpermute_b32 v15, v219, v14
	s_waitcnt lgkmcnt(0)
	v_add_f32_e32 v14, v14, v15
	v_fmamk_f32 v14, v14, 0x3a800000, v201
	v_cmp_gt_f32_e32 vcc, s62, v14
	v_mul_f32_e32 v15, 0x4b800000, v14
	s_nop 0
	v_cndmask_b32_e32 v14, v14, v15, vcc
	v_rsq_f32_e32 v14, v14
	s_nop 0
	v_mul_f32_e32 v15, 0x45800000, v14
	v_cndmask_b32_e32 v52, v14, v15, vcc
	v_pk_mul_f32 v[14:15], v[16:17], v[52:53] op_sel_hi:[1,0]
	s_and_b64 vcc, exec, s[30:31]
	v_pk_fma_f32 v[14:15], v[2:3], v[14:15], v[6:7]
	v_pk_mul_f32 v[2:3], v[60:61], v[52:53] op_sel_hi:[1,0]
	s_nop 0
	v_pk_fma_f32 v[16:17], v[4:5], v[2:3], v[8:9]
	v_pk_mul_f32 v[2:3], v[44:45], v[52:53] op_sel_hi:[1,0]
	v_pk_mul_f32 v[4:5], v[50:51], v[52:53] op_sel_hi:[1,0]
	v_pk_fma_f32 v[10:11], v[10:11], v[2:3], v[18:19]
	v_pk_mul_f32 v[2:3], v[42:43], v[52:53] op_sel_hi:[1,0]
	s_waitcnt vmcnt(0)
	v_pk_fma_f32 v[4:5], v[32:33], v[4:5], v[36:37]
	v_pk_fma_f32 v[12:13], v[12:13], v[2:3], v[20:21]
	v_pk_mul_f32 v[2:3], v[56:57], v[52:53] op_sel_hi:[1,0]
	s_nop 0
	v_pk_fma_f32 v[6:7], v[22:23], v[2:3], v[26:27]
	v_pk_mul_f32 v[2:3], v[58:59], v[52:53] op_sel_hi:[1,0]
	s_nop 0
	v_pk_fma_f32 v[8:9], v[24:25], v[2:3], v[28:29]
	v_pk_mul_f32 v[2:3], v[48:49], v[52:53] op_sel_hi:[1,0]
	s_nop 0
	v_pk_fma_f32 v[2:3], v[30:31], v[2:3], v[34:35]
	s_cbranch_vccz .LBB0_873
	v_add_f32_e32 v18, 0, v14
	v_add_f32_e32 v18, v15, v18
	v_add_f32_e32 v18, v16, v18
	v_add_f32_e32 v18, v17, v18
	v_add_f32_e32 v18, v10, v18
	v_add_f32_e32 v18, v11, v18
	v_add_f32_e32 v18, v12, v18
	v_add_f32_e32 v18, v13, v18
	v_add_f32_e32 v18, v6, v18
	v_add_f32_e32 v18, v7, v18
	v_add_f32_e32 v18, v8, v18
	v_add_f32_e32 v18, v9, v18
	v_add_f32_e32 v18, v2, v18
	v_add_f32_e32 v18, v3, v18
	v_add_f32_e32 v18, v4, v18
	v_add_f32_e32 v18, v5, v18
	ds_bpermute_b32 v19, v215, v18
	v_add_u32_e32 v22, 3, v46
	global_store_dwordx4 v[40:41], v[14:17], off
	global_store_dwordx4 v[40:41], v[10:13], off offset:1024
	s_waitcnt lgkmcnt(0)
	v_add_f32_e32 v20, v18, v19
	ds_bpermute_b32 v21, v214, v20
	v_mov_b64_e32 v[18:19], s[16:17]
	v_mad_u64_u32 v[18:19], s[0:1], v22, s63, v[18:19]
	v_lshl_add_u64 v[48:49], v[18:19], 0, v[0:1]
	s_waitcnt lgkmcnt(0)
	v_add_f32_e32 v20, v20, v21
	ds_bpermute_b32 v21, v216, v20
	v_add_co_u32_e32 v18, vcc, s58, v48
	s_mov_b64 s[0:1], 0x1000
	s_nop 0
	v_addc_co_u32_e32 v19, vcc, 0, v49, vcc
	s_waitcnt lgkmcnt(0)
	v_add_f32_e32 v0, v20, v21
	ds_bpermute_b32 v26, v217, v0
	v_lshl_add_u64 v[30:31], v[48:49], 0, s[0:1]
	global_load_dwordx4 v[18:21], v[18:19], off
	s_nop 0
	global_load_dwordx4 v[22:25], v[30:31], off offset:1024
	s_nop 0
	global_store_dwordx4 v[40:41], v[6:9], off offset:2048
	global_store_dwordx4 v[40:41], v[2:5], off offset:3072
	s_mov_b64 s[0:1], 0
	s_waitcnt lgkmcnt(0)
	v_add_f32_e32 v0, v0, v26
	ds_bpermute_b32 v26, v218, v0
	s_waitcnt lgkmcnt(0)
	v_add_f32_e32 v0, v0, v26
	ds_bpermute_b32 v44, v219, v0
	global_load_dwordx4 v[26:29], v[30:31], off offset:2048
	s_nop 0
	global_load_dwordx4 v[30:33], v[30:31], off offset:3072
	s_nop 0
	global_load_dwordx4 v[34:37], v[48:49], off
	global_load_dwordx4 v[40:43], v[48:49], off offset:1024
	s_waitcnt lgkmcnt(0)
	v_add_f32_e32 v0, v0, v44
	global_load_dwordx4 v[44:47], v[48:49], off offset:2048
	v_mul_f32_e32 v0, 0x3a800000, v0
	global_load_dwordx4 v[48:51], v[48:49], off offset:3072
	v_pk_add_f32 v[54:55], v[14:15], v[0:1] op_sel_hi:[1,0] neg_lo:[0,1] neg_hi:[0,1]
	v_pk_add_f32 v[52:53], v[16:17], v[0:1] op_sel_hi:[1,0] neg_lo:[0,1] neg_hi:[0,1]
	v_pk_mul_f32 v[60:61], v[54:55], v[54:55]
	v_pk_add_f32 v[56:57], v[12:13], v[0:1] op_sel_hi:[1,0] neg_lo:[0,1] neg_hi:[0,1]
	v_pk_mul_f32 v[58:59], v[52:53], v[52:53]
	v_pk_add_f32 v[64:65], v[10:11], v[0:1] op_sel_hi:[1,0] neg_lo:[0,1] neg_hi:[0,1]
	v_pk_add_f32 v[68:69], v[8:9], v[0:1] op_sel_hi:[1,0] neg_lo:[0,1] neg_hi:[0,1]
	v_pk_add_f32 v[72:73], v[6:7], v[0:1] op_sel_hi:[1,0] neg_lo:[0,1] neg_hi:[0,1]
	v_pk_add_f32 v[76:77], v[4:5], v[0:1] op_sel_hi:[1,0] neg_lo:[0,1] neg_hi:[0,1]
	v_pk_add_f32 v[80:81], v[2:3], v[0:1] op_sel_hi:[1,0] neg_lo:[0,1] neg_hi:[0,1]
	v_add_f32_e32 v0, v60, v61
	v_add_f32_e32 v0, v58, v0
	v_pk_mul_f32 v[66:67], v[64:65], v[64:65]
	v_add_f32_e32 v0, v59, v0
	v_add_f32_e32 v0, v66, v0
	v_pk_mul_f32 v[62:63], v[56:57], v[56:57]
	v_add_f32_e32 v0, v67, v0
	v_add_f32_e32 v0, v62, v0
	v_pk_mul_f32 v[74:75], v[72:73], v[72:73]
	v_add_f32_e32 v0, v63, v0
	v_add_f32_e32 v0, v74, v0
	v_pk_mul_f32 v[70:71], v[68:69], v[68:69]
	v_add_f32_e32 v0, v75, v0
	v_add_f32_e32 v0, v70, v0
	v_pk_mul_f32 v[82:83], v[80:81], v[80:81]
	v_add_f32_e32 v0, v71, v0
	v_add_f32_e32 v0, v82, v0
	v_pk_mul_f32 v[78:79], v[76:77], v[76:77]
	v_add_f32_e32 v0, v83, v0
	v_add_f32_e32 v0, v78, v0
	v_add_f32_e32 v0, v79, v0
	ds_bpermute_b32 v58, v215, v0
	s_waitcnt lgkmcnt(0)
	v_add_f32_e32 v0, v0, v58
	ds_bpermute_b32 v58, v214, v0
	s_waitcnt lgkmcnt(0)
	v_add_f32_e32 v0, v0, v58
	ds_bpermute_b32 v58, v216, v0
	s_waitcnt lgkmcnt(0)
	v_add_f32_e32 v0, v0, v58
	ds_bpermute_b32 v58, v217, v0
	s_waitcnt lgkmcnt(0)
	v_add_f32_e32 v0, v0, v58
	ds_bpermute_b32 v58, v218, v0
	s_waitcnt lgkmcnt(0)
	v_add_f32_e32 v0, v0, v58
	ds_bpermute_b32 v58, v219, v0
	s_waitcnt vmcnt(9)
	v_pk_add_f32 v[18:19], v[18:19], 1.0 op_sel_hi:[1,0]
	v_pk_add_f32 v[20:21], v[20:21], 1.0 op_sel_hi:[1,0]
	s_waitcnt vmcnt(8)
	v_pk_add_f32 v[22:23], v[22:23], 1.0 op_sel_hi:[1,0]
	v_pk_add_f32 v[24:25], v[24:25], 1.0 op_sel_hi:[1,0]
	s_waitcnt lgkmcnt(0)
	v_add_f32_e32 v0, v0, v58
	v_fmamk_f32 v0, v0, 0x3a800000, v201
	v_mul_f32_e32 v58, 0x4b800000, v0
	v_cmp_gt_f32_e32 vcc, s62, v0
	s_waitcnt vmcnt(5)
	v_pk_add_f32 v[28:29], v[28:29], 1.0 op_sel_hi:[1,0]
	s_waitcnt vmcnt(4)
	v_pk_add_f32 v[30:31], v[30:31], 1.0 op_sel_hi:[1,0]
	v_cndmask_b32_e32 v0, v0, v58, vcc
	v_rsq_f32_e32 v0, v0
	v_pk_add_f32 v[32:33], v[32:33], 1.0 op_sel_hi:[1,0]
	v_pk_add_f32 v[26:27], v[26:27], 1.0 op_sel_hi:[1,0]
	v_mul_f32_e32 v58, 0x45800000, v0
	v_cndmask_b32_e32 v0, v0, v58, vcc
	v_pk_mul_f32 v[54:55], v[54:55], v[0:1] op_sel_hi:[1,0]
	v_pk_mul_f32 v[52:53], v[52:53], v[0:1] op_sel_hi:[1,0]
	s_waitcnt vmcnt(3)
	v_pk_fma_f32 v[18:19], v[18:19], v[54:55], v[34:35]
	v_pk_mul_f32 v[34:35], v[68:69], v[0:1] op_sel_hi:[1,0]
	v_pk_mul_f32 v[58:59], v[64:65], v[0:1] op_sel_hi:[1,0]
	s_waitcnt vmcnt(1)
	v_pk_fma_f32 v[28:29], v[34:35], v[28:29], v[46:47]
	v_pk_mul_f32 v[34:35], v[80:81], v[0:1] op_sel_hi:[1,0]
	v_pk_mul_f32 v[56:57], v[56:57], v[0:1] op_sel_hi:[1,0]
	v_pk_fma_f32 v[20:21], v[20:21], v[52:53], v[36:37]
	s_waitcnt vmcnt(0)
	v_pk_fma_f32 v[30:31], v[34:35], v[30:31], v[48:49]
	v_pk_mul_f32 v[34:35], v[76:77], v[0:1] op_sel_hi:[1,0]
	v_pk_mul_f32 v[60:61], v[72:73], v[0:1] op_sel_hi:[1,0]
	v_pk_fma_f32 v[22:23], v[22:23], v[58:59], v[40:41]
	v_pk_fma_f32 v[24:25], v[24:25], v[56:57], v[42:43]
	v_pk_fma_f32 v[32:33], v[34:35], v[32:33], v[50:51]
	v_lshl_add_u64 v[34:35], v[38:39], 1, v[138:139]
	v_cvt_pk_bf16_f32 v18, v18, v19
	v_cvt_pk_bf16_f32 v19, v20, v21
	v_pk_fma_f32 v[26:27], v[26:27], v[60:61], v[44:45]
	global_store_dwordx2 v[34:35], v[18:19], off
	v_cvt_pk_bf16_f32 v18, v22, v23
	v_cvt_pk_bf16_f32 v19, v24, v25
	global_store_dwordx2 v[34:35], v[18:19], off offset:512
	v_cvt_pk_bf16_f32 v18, v26, v27
	v_cvt_pk_bf16_f32 v19, v28, v29
	global_store_dwordx2 v[34:35], v[18:19], off offset:1024
	v_cvt_pk_bf16_f32 v18, v30, v31
	v_cvt_pk_bf16_f32 v19, v32, v33
	global_store_dwordx2 v[34:35], v[18:19], off offset:1536

	.amdhsa_kernel _Z14fwd_megakernel6Params
		.amdhsa_group_segment_fixed_size 78880
		.amdhsa_private_segment_fixed_size 0
		.amdhsa_kernarg_size 480
		.amdhsa_user_sgpr_count 2
		.amdhsa_user_sgpr_dispatch_ptr 0
		.amdhsa_user_sgpr_queue_ptr 0
		.amdhsa_user_sgpr_kernarg_segment_ptr 1
		.amdhsa_user_sgpr_dispatch_id 0
		.amdhsa_user_sgpr_kernarg_preload_length 0
		.amdhsa_user_sgpr_kernarg_preload_offset 0
		.amdhsa_user_sgpr_private_segment_size 0
		.amdhsa_uses_dynamic_stack 0
		.amdhsa_enable_private_segment 0
		.amdhsa_system_sgpr_workgroup_id_x 1
		.amdhsa_system_sgpr_workgroup_id_y 0
		.amdhsa_system_sgpr_workgroup_id_z 0
		.amdhsa_system_sgpr_workgroup_info 0
		.amdhsa_system_vgpr_workitem_id 2
		.amdhsa_next_free_vgpr 256
		.amdhsa_next_free_sgpr 102
		.amdhsa_accum_offset 256
		.amdhsa_reserve_vcc 1
		.amdhsa_float_round_mode_32 0
		.amdhsa_float_round_mode_16_64 0
		.amdhsa_float_denorm_mode_32 3
		.amdhsa_float_denorm_mode_16_64 3
		.amdhsa_dx10_clamp 1
		.amdhsa_ieee_mode 1
		.amdhsa_fp16_overflow 0
		.amdhsa_tg_split 0
		.amdhsa_exception_fp_ieee_invalid_op 0
		.amdhsa_exception_fp_denorm_src 0
		.amdhsa_exception_fp_ieee_div_zero 0
		.amdhsa_exception_fp_ieee_overflow 0
		.amdhsa_exception_fp_ieee_underflow 0
		.amdhsa_exception_fp_ieee_inexact 0
		.amdhsa_exception_int_div_zero 0
	.end_amdhsa_kernel

amdhsa.kernels:
  - .agpr_count:     0
    .args:
      - .offset:         0
        .size:           224
        .value_kind:     by_value
      - .offset:         224
        .size:           4
        .value_kind:     hidden_block_count_x
      - .offset:         228
        .size:           4
        .value_kind:     hidden_block_count_y
      - .offset:         232
        .size:           4
        .value_kind:     hidden_block_count_z
      - .offset:         236
        .size:           2
        .value_kind:     hidden_group_size_x
      - .offset:         238
        .size:           2
        .value_kind:     hidden_group_size_y
      - .offset:         240
        .size:           2
        .value_kind:     hidden_group_size_z
      - .offset:         242
        .size:           2
        .value_kind:     hidden_remainder_x
      - .offset:         244
        .size:           2
        .value_kind:     hidden_remainder_y
      - .offset:         246
        .size:           2
        .value_kind:     hidden_remainder_z
      - .offset:         264
        .size:           8
        .value_kind:     hidden_global_offset_x
      - .offset:         272
        .size:           8
        .value_kind:     hidden_global_offset_y
      - .offset:         280
        .size:           8
        .value_kind:     hidden_global_offset_z
      - .offset:         288
        .size:           2
        .value_kind:     hidden_grid_dims
      - .offset:         312
        .size:           8
        .value_kind:     hidden_multigrid_sync_arg
    .group_segment_fixed_size: 78880
    .kernarg_segment_align: 8
    .kernarg_segment_size: 480
    .language:       OpenCL C
    .language_version:
      - 2
      - 0
    .max_flat_workgroup_size: 256
    .name:           _Z14fwd_megakernel6Params
    .private_segment_fixed_size: 0
    .sgpr_count:     108
    .sgpr_spill_count: 144
    .symbol:         _Z14fwd_megakernel6Params.kd
    .uniform_work_group_size: 1
    .uses_dynamic_stack: false
    .vgpr_count:     256
    .vgpr_spill_count: 0
    .wavefront_size: 64
